# the five steady K-loop heads aligned to 64-byte instruction-cache lines with .p2align 6 (padding s_nops run once per tile in a load segment)
# speedup vs baseline: 1.0041x; 1.0041x over previous
; #define PG8_STAGE(bufoff, gbase, voff) do { _Pragma("unroll") for (int _i = 0; _i < 2; ++_i) { \
;         const unsigned _m0 = ldsb + (unsigned)((bufoff) + _i * 8192); const char* _gb = (const char*)(gbase); \
;         asm volatile("s_mov_b32 m0, %0\n\ts_nop 0\n\tglobal_load_lds_dwordx4 %1, %2" :: "s"(_m0), "v"((voff)[_i]), "s"(_gb) : "m0", "memory"); } } while (0)
; #define PG8_LDA(dst, b, h) do { _Pragma("unroll") for (int m = 0; m < 4; ++m) _Pragma("unroll") for (int k = 0; k < 2; ++k) dst[m][k] = *(const LAS bf16x8*)(lds + PG8_SA(b, h) + aoff + m * 2048 + k * 1024); } while (0)
; #define PG8_LDB(dst, b, h) do { _Pragma("unroll") for (int n = 0; n < 2; ++n) _Pragma("unroll") for (int k = 0; k < 2; ++k) dst[n][k] = *(const LAS bf16x8*)(lds + PG8_SB(b, h) + boff + n * 2048 + k * 1024); } while (0)
; #define PG8_MMA(ai, bj, At, Bt) do { __builtin_amdgcn_s_setprio(1); _Pragma("unroll") for (int m = 0; m < 4; ++m) _Pragma("unroll") for (int n = 0; n < 2; ++n) _Pragma("unroll") for (int k = 0; k < 2; ++k) \
;         acc[ai][bj][m][n] = __builtin_amdgcn_mfma_f32_16x16x32_bf16(Bt[n][k], At[m][k], acc[ai][bj][m][n], 0, 0, 0); __builtin_amdgcn_s_setprio(0); } while (0)
; #define PG8_WAIT_V(n) asm volatile("s_waitcnt vmcnt(" #n ")" ::: "memory")
; #define PG8_WAIT_L(n) asm volatile("s_waitcnt lgkmcnt(" #n ")" ::: "memory")
; #define PG8_BAR __builtin_amdgcn_s_barrier()
; #define PG8_SCHED __builtin_amdgcn_sched_barrier(0)
; template <class Epi, bool ALIGN_EPI>
; __device__ __forceinline__ void gemm_phase(LAS unsigned char* lds, const Gemm g, const StaticOrder& S, const Epi& E) {
;     ...
;             PG8_LDB(B0, 0, 0); PG8_LDB(B1, 0, 1); PG8_SCHED; PG8_LDA(At, 0, 0); PG8_STAGE(PG8_SA(1, 1), a1 + hstepA, voffA);
;             PG8_WAIT_V(8); PG8_WAIT_L(0); PG8_BAR; PG8_MMA(0, 0, At, B0); PG8_MMA(0, 1, At, B1); PG8_BAR; PG8_SCHED;
;             PG8_LDA(At, 0, 1); PG8_STAGE(PG8_SB(0, 0), b2, voffB); PG8_STAGE(PG8_SB(0, 1), b2 + hstepB, voffB); PG8_STAGE(PG8_SA(0, 0), a2, voffA);
;             PG8_WAIT_V(8); PG8_WAIT_L(0); PG8_BAR; PG8_MMA(1, 0, At, B0); PG8_MMA(1, 1, At, B1); PG8_BAR; PG8_SCHED;
.LBB0_150:
	s_add_u32 s4, s48, 0x100
	s_addc_u32 s5, s49, 0
	s_add_u32 s37, s54, 0x100
	s_addc_u32 s44, s55, 0
	s_mov_b32 s45, 0
	s_waitcnt lgkmcnt(0)
	s_add_i32 s51, s45, 2
	s_cmp_eq_u32 s67, s45
	s_cselect_b32 s56, s0, s37
	s_cselect_b32 s57, s1, s44
	s_cselect_b32 s54, s94, s4
	s_cselect_b32 s55, s95, s5
	s_add_u32 s48, s56, 0x80
	s_addc_u32 s49, s57, 0
	s_add_u32 s45, s37, s15
	s_addc_u32 s59, s44, 0
	s_add_u32 s58, s45, 0xffffff80
	s_addc_u32 s59, s59, -1
	s_mov_b32 m0, s68
	s_nop 0
	global_load_lds_dwordx4 v0, s[58:59]
	s_nop 0
	s_mov_b32 m0, s85
	s_nop 0
	global_load_lds_dwordx4 v240, s[58:59]
	s_waitcnt vmcnt(8)
	s_waitcnt lgkmcnt(0)
	s_setprio 1
	s_barrier
	v_mfma_f32_16x16x32_bf16 v[172:175], v[108:111], v[156:159], 0
	v_mfma_f32_16x16x32_bf16 v[172:175], v[120:123], v[160:163], v[172:175]
	v_mfma_f32_16x16x32_bf16 v[168:171], v[128:131], v[156:159], 0
	v_mfma_f32_16x16x32_bf16 v[168:171], v[132:135], v[160:163], v[168:171]
	v_mfma_f32_16x16x32_bf16 v[140:143], v[136:139], v[156:159], 0
	v_mfma_f32_16x16x32_bf16 v[140:143], v[144:147], v[160:163], v[140:143]
	v_mfma_f32_16x16x32_bf16 v[124:127], v[148:151], v[156:159], 0
	v_mfma_f32_16x16x32_bf16 v[124:127], v[152:155], v[160:163], v[124:127]
	v_mfma_f32_16x16x32_bf16 v[100:103], v[148:151], v[164:167], 0
	v_mfma_f32_16x16x32_bf16 v[100:103], v[152:155], v[176:179], v[100:103]
	v_mfma_f32_16x16x32_bf16 v[104:107], v[136:139], v[164:167], 0
	v_mfma_f32_16x16x32_bf16 v[104:107], v[144:147], v[176:179], v[104:107]
	v_mfma_f32_16x16x32_bf16 v[112:115], v[128:131], v[164:167], 0
	v_mfma_f32_16x16x32_bf16 v[112:115], v[132:135], v[176:179], v[112:115]
	v_mfma_f32_16x16x32_bf16 v[116:119], v[108:111], v[164:167], 0
	v_mfma_f32_16x16x32_bf16 v[116:119], v[120:123], v[176:179], v[116:119]
	v_mfma_f32_16x16x32_bf16 v[96:99], v[108:111], v[180:183], 0
	v_mfma_f32_16x16x32_bf16 v[96:99], v[120:123], v[184:187], v[96:99]
	v_mfma_f32_16x16x32_bf16 v[92:95], v[128:131], v[180:183], 0
	v_mfma_f32_16x16x32_bf16 v[92:95], v[132:135], v[184:187], v[92:95]
	v_mfma_f32_16x16x32_bf16 v[88:91], v[136:139], v[180:183], 0
	v_mfma_f32_16x16x32_bf16 v[88:91], v[144:147], v[184:187], v[88:91]
	v_mfma_f32_16x16x32_bf16 v[84:87], v[148:151], v[180:183], 0
	v_mfma_f32_16x16x32_bf16 v[84:87], v[152:155], v[184:187], v[84:87]
	v_mfma_f32_16x16x32_bf16 v[68:71], v[148:151], v[188:191], 0
	v_mfma_f32_16x16x32_bf16 v[68:71], v[152:155], v[202:205], v[68:71]
	v_mfma_f32_16x16x32_bf16 v[72:75], v[136:139], v[188:191], 0
	v_mfma_f32_16x16x32_bf16 v[72:75], v[144:147], v[202:205], v[72:75]
	v_mfma_f32_16x16x32_bf16 v[76:79], v[128:131], v[188:191], 0
	v_mfma_f32_16x16x32_bf16 v[76:79], v[132:135], v[202:205], v[76:79]
	v_mfma_f32_16x16x32_bf16 v[80:83], v[108:111], v[188:191], 0
	v_mfma_f32_16x16x32_bf16 v[80:83], v[120:123], v[202:205], v[80:83]
	s_barrier
	s_setprio 0
	ds_read_b128 v[156:159], v245 offset:16384
	ds_read_b128 v[160:163], v245 offset:17408
	ds_read_b128 v[164:167], v245 offset:18432
	ds_read_b128 v[176:179], v245 offset:19456
	ds_read_b128 v[180:183], v245 offset:20480
	ds_read_b128 v[184:187], v245 offset:21504
	ds_read_b128 v[188:191], v245 offset:22528
	ds_read_b128 v[202:205], v245 offset:23552
	s_mov_b32 m0, s27
	s_nop 0
	global_load_lds_dwordx4 v195, s[54:55]
	s_add_u32 s58, s54, s15
	s_mov_b32 m0, s28
	s_nop 0
	global_load_lds_dwordx4 v241, s[54:55]
	s_addc_u32 s59, s55, 0
	s_mov_b32 m0, s29
	s_nop 0
	global_load_lds_dwordx4 v195, s[58:59]
	s_nop 0
	s_mov_b32 m0, s30
	s_nop 0
	global_load_lds_dwordx4 v241, s[58:59]
	s_nop 0
	s_mov_b32 m0, s26
	s_nop 0
	global_load_lds_dwordx4 v0, s[56:57]
	s_nop 0
	s_mov_b32 m0, s31
	s_nop 0
	global_load_lds_dwordx4 v240, s[56:57]
	s_waitcnt vmcnt(8)
	s_waitcnt lgkmcnt(0)
	s_setprio 1
	s_barrier
	v_mfma_f32_16x16x32_bf16 v[64:67], v[108:111], v[156:159], 0
	v_mfma_f32_16x16x32_bf16 v[64:67], v[120:123], v[160:163], v[64:67]
	v_mfma_f32_16x16x32_bf16 v[60:63], v[128:131], v[156:159], 0
	v_mfma_f32_16x16x32_bf16 v[60:63], v[132:135], v[160:163], v[60:63]
	v_mfma_f32_16x16x32_bf16 v[56:59], v[136:139], v[156:159], 0
	v_mfma_f32_16x16x32_bf16 v[56:59], v[144:147], v[160:163], v[56:59]
	v_mfma_f32_16x16x32_bf16 v[52:55], v[148:151], v[156:159], 0
	v_mfma_f32_16x16x32_bf16 v[52:55], v[152:155], v[160:163], v[52:55]
	v_mfma_f32_16x16x32_bf16 v[36:39], v[148:151], v[164:167], 0
	v_mfma_f32_16x16x32_bf16 v[36:39], v[152:155], v[176:179], v[36:39]
	v_mfma_f32_16x16x32_bf16 v[40:43], v[136:139], v[164:167], 0
	v_mfma_f32_16x16x32_bf16 v[40:43], v[144:147], v[176:179], v[40:43]
	v_mfma_f32_16x16x32_bf16 v[44:47], v[128:131], v[164:167], 0
	v_mfma_f32_16x16x32_bf16 v[44:47], v[132:135], v[176:179], v[44:47]
	v_mfma_f32_16x16x32_bf16 v[48:51], v[108:111], v[164:167], 0
	v_mfma_f32_16x16x32_bf16 v[48:51], v[120:123], v[176:179], v[48:51]
	v_mfma_f32_16x16x32_bf16 v[32:35], v[108:111], v[180:183], 0
	v_mfma_f32_16x16x32_bf16 v[32:35], v[120:123], v[184:187], v[32:35]
	v_mfma_f32_16x16x32_bf16 v[28:31], v[128:131], v[180:183], 0
	v_mfma_f32_16x16x32_bf16 v[28:31], v[132:135], v[184:187], v[28:31]
	v_mfma_f32_16x16x32_bf16 v[24:27], v[136:139], v[180:183], 0
	v_mfma_f32_16x16x32_bf16 v[24:27], v[144:147], v[184:187], v[24:27]
	v_mfma_f32_16x16x32_bf16 v[20:23], v[148:151], v[180:183], 0
	v_mfma_f32_16x16x32_bf16 v[20:23], v[152:155], v[184:187], v[20:23]
	v_mfma_f32_16x16x32_bf16 v[4:7], v[148:151], v[188:191], 0
	v_mfma_f32_16x16x32_bf16 v[4:7], v[152:155], v[202:205], v[4:7]
	v_mfma_f32_16x16x32_bf16 v[8:11], v[136:139], v[188:191], 0
	v_mfma_f32_16x16x32_bf16 v[8:11], v[144:147], v[202:205], v[8:11]
	v_mfma_f32_16x16x32_bf16 v[12:15], v[128:131], v[188:191], 0
	v_mfma_f32_16x16x32_bf16 v[12:15], v[132:135], v[202:205], v[12:15]
	v_mfma_f32_16x16x32_bf16 v[16:19], v[108:111], v[188:191], 0
	v_mfma_f32_16x16x32_bf16 v[16:19], v[120:123], v[202:205], v[16:19]
	s_barrier
; #define PG8_STAGE(bufoff, gbase, voff) do { _Pragma("unroll") for (int _i = 0; _i < 2; ++_i) { \
;         const unsigned _m0 = ldsb + (unsigned)((bufoff) + _i * 8192); const char* _gb = (const char*)(gbase); \
;         asm volatile("s_mov_b32 m0, %0\n\ts_nop 0\n\tglobal_load_lds_dwordx4 %1, %2" :: "s"(_m0), "v"((voff)[_i]), "s"(_gb) : "m0", "memory"); } } while (0)
; #define PG8_LDA(dst, b, h) do { _Pragma("unroll") for (int m = 0; m < 4; ++m) _Pragma("unroll") for (int k = 0; k < 2; ++k) dst[m][k] = *(const LAS bf16x8*)(lds + PG8_SA(b, h) + aoff + m * 2048 + k * 1024); } while (0)
; #define PG8_LDB(dst, b, h) do { _Pragma("unroll") for (int n = 0; n < 2; ++n) _Pragma("unroll") for (int k = 0; k < 2; ++k) dst[n][k] = *(const LAS bf16x8*)(lds + PG8_SB(b, h) + boff + n * 2048 + k * 1024); } while (0)
; #define PG8_MMA(ai, bj, At, Bt) do { __builtin_amdgcn_s_setprio(1); _Pragma("unroll") for (int m = 0; m < 4; ++m) _Pragma("unroll") for (int n = 0; n < 2; ++n) _Pragma("unroll") for (int k = 0; k < 2; ++k) \
;         acc[ai][bj][m][n] = __builtin_amdgcn_mfma_f32_16x16x32_bf16(Bt[n][k], At[m][k], acc[ai][bj][m][n], 0, 0, 0); __builtin_amdgcn_s_setprio(0); } while (0)
; #define PG8_WAIT_V(n) asm volatile("s_waitcnt vmcnt(" #n ")" ::: "memory")
; #define PG8_WAIT_L(n) asm volatile("s_waitcnt lgkmcnt(" #n ")" ::: "memory")
; #define PG8_BAR __builtin_amdgcn_s_barrier()
; #define PG8_SCHED __builtin_amdgcn_sched_barrier(0)
; template <class Epi, bool ALIGN_EPI>
; __device__ __forceinline__ void gemm_phase(LAS unsigned char* lds, const Gemm g, const StaticOrder& S, const Epi& E) {
;     ...
;             PG8_WAIT_V(8); PG8_WAIT_L(0); PG8_BAR; PG8_MMA(1, 0, At, B0); PG8_MMA(1, 1, At, B1); PG8_BAR; PG8_SCHED;
;             PG8_LDB(B0, 1, 0); PG8_LDB(B1, 1, 1); PG8_SCHED; PG8_LDA(At, 1, 0); PG8_STAGE(PG8_SA(0, 1), a2 + hstepA, voffA);
;             PG8_WAIT_V(8); PG8_WAIT_L(0); PG8_BAR; PG8_MMA(0, 0, At, B0); PG8_MMA(0, 1, At, B1); PG8_BAR; PG8_SCHED;
;             PG8_LDA(At, 1, 1); PG8_STAGE(PG8_SB(1, 0), b3, voffB); PG8_STAGE(PG8_SB(1, 1), b3 + hstepB, voffB); PG8_STAGE(PG8_SA(1, 0), a3, voffA);
;             PG8_WAIT_V(8); PG8_WAIT_L(0); PG8_BAR; PG8_MMA(1, 0, At, B0); PG8_MMA(1, 1, At, B1); PG8_BAR; PG8_SCHED;
;         }
	s_setprio 0
	v_add_u32_e32 v132, 0x18000, v244
	v_add_u32_e32 v152, 0x1c000, v244
	ds_read_b128 v[108:111], v132
	ds_read_b128 v[120:123], v132 offset:1024
	ds_read_b128 v[128:131], v132 offset:2048
	ds_read_b128 v[132:135], v132 offset:3072
	ds_read_b128 v[136:139], v152
	ds_read_b128 v[144:147], v152 offset:1024
	ds_read_b128 v[148:151], v152 offset:2048
	ds_read_b128 v[152:155], v152 offset:3072
	ds_read_b128 v[156:159], v245 offset:32768
	ds_read_b128 v[160:163], v245 offset:33792
	ds_read_b128 v[164:167], v245 offset:34816
	ds_read_b128 v[176:179], v245 offset:35840
	ds_read_b128 v[180:183], v245 offset:36864
	ds_read_b128 v[184:187], v245 offset:37888
	ds_read_b128 v[188:191], v245 offset:38912
	ds_read_b128 v[202:205], v245 offset:39936
	s_add_u32 s56, s56, s15
	s_addc_u32 s57, s57, 0
	s_mov_b32 m0, s41
	s_nop 0
	global_load_lds_dwordx4 v0, s[56:57]
	s_nop 0
	s_mov_b32 m0, s42
	s_nop 0
	global_load_lds_dwordx4 v240, s[56:57]
	s_waitcnt vmcnt(8)
	s_waitcnt lgkmcnt(0)
	s_setprio 1
	s_barrier
	v_mfma_f32_16x16x32_bf16 v[172:175], v[108:111], v[156:159], v[172:175]
	v_mfma_f32_16x16x32_bf16 v[172:175], v[120:123], v[160:163], v[172:175]
	v_mfma_f32_16x16x32_bf16 v[168:171], v[128:131], v[156:159], v[168:171]
	v_mfma_f32_16x16x32_bf16 v[168:171], v[132:135], v[160:163], v[168:171]
	v_mfma_f32_16x16x32_bf16 v[140:143], v[136:139], v[156:159], v[140:143]
	v_mfma_f32_16x16x32_bf16 v[140:143], v[144:147], v[160:163], v[140:143]
	v_mfma_f32_16x16x32_bf16 v[124:127], v[148:151], v[156:159], v[124:127]
	v_mfma_f32_16x16x32_bf16 v[124:127], v[152:155], v[160:163], v[124:127]
	v_mfma_f32_16x16x32_bf16 v[100:103], v[148:151], v[164:167], v[100:103]
	v_mfma_f32_16x16x32_bf16 v[100:103], v[152:155], v[176:179], v[100:103]
	v_mfma_f32_16x16x32_bf16 v[104:107], v[136:139], v[164:167], v[104:107]
	v_mfma_f32_16x16x32_bf16 v[104:107], v[144:147], v[176:179], v[104:107]
	v_mfma_f32_16x16x32_bf16 v[112:115], v[128:131], v[164:167], v[112:115]
	v_mfma_f32_16x16x32_bf16 v[112:115], v[132:135], v[176:179], v[112:115]
	v_mfma_f32_16x16x32_bf16 v[116:119], v[108:111], v[164:167], v[116:119]
	v_mfma_f32_16x16x32_bf16 v[116:119], v[120:123], v[176:179], v[116:119]
	v_mfma_f32_16x16x32_bf16 v[96:99], v[108:111], v[180:183], v[96:99]
	v_mfma_f32_16x16x32_bf16 v[96:99], v[120:123], v[184:187], v[96:99]
	v_mfma_f32_16x16x32_bf16 v[92:95], v[128:131], v[180:183], v[92:95]
	v_mfma_f32_16x16x32_bf16 v[92:95], v[132:135], v[184:187], v[92:95]
	v_mfma_f32_16x16x32_bf16 v[88:91], v[136:139], v[180:183], v[88:91]
	v_mfma_f32_16x16x32_bf16 v[88:91], v[144:147], v[184:187], v[88:91]
	v_mfma_f32_16x16x32_bf16 v[84:87], v[148:151], v[180:183], v[84:87]
	v_mfma_f32_16x16x32_bf16 v[84:87], v[152:155], v[184:187], v[84:87]
	v_mfma_f32_16x16x32_bf16 v[68:71], v[148:151], v[188:191], v[68:71]
	v_mfma_f32_16x16x32_bf16 v[68:71], v[152:155], v[202:205], v[68:71]
	v_mfma_f32_16x16x32_bf16 v[72:75], v[136:139], v[188:191], v[72:75]
	v_mfma_f32_16x16x32_bf16 v[72:75], v[144:147], v[202:205], v[72:75]
	v_mfma_f32_16x16x32_bf16 v[76:79], v[128:131], v[188:191], v[76:79]
	v_mfma_f32_16x16x32_bf16 v[76:79], v[132:135], v[202:205], v[76:79]
	v_mfma_f32_16x16x32_bf16 v[80:83], v[108:111], v[188:191], v[80:83]
	v_mfma_f32_16x16x32_bf16 v[80:83], v[120:123], v[202:205], v[80:83]
	s_barrier
	s_setprio 0
	ds_read_b128 v[156:159], v245 offset:49152
	ds_read_b128 v[160:163], v245 offset:50176
	ds_read_b128 v[164:167], v245 offset:51200
	ds_read_b128 v[176:179], v245 offset:52224
	ds_read_b128 v[180:183], v245 offset:53248
	ds_read_b128 v[184:187], v245 offset:54272
	ds_read_b128 v[188:191], v245 offset:55296
	ds_read_b128 v[202:205], v245 offset:56320
	s_add_u32 s54, s54, 0x80
	s_addc_u32 s55, s55, 0
	s_mov_b32 m0, s46
	s_nop 0
	global_load_lds_dwordx4 v195, s[54:55]
	s_nop 0
	s_mov_b32 m0, s50
	s_nop 0
	global_load_lds_dwordx4 v241, s[54:55]
	s_add_u32 s54, s58, 0x80
	s_addc_u32 s55, s59, 0
	s_mov_b32 m0, s61
	s_nop 0
	global_load_lds_dwordx4 v195, s[54:55]
	s_nop 0
	s_mov_b32 m0, s65
	s_nop 0
	global_load_lds_dwordx4 v241, s[54:55]
	s_nop 0
	s_mov_b32 m0, s53
	s_nop 0
	global_load_lds_dwordx4 v0, s[48:49]
	s_nop 0
	s_mov_b32 m0, s60
	s_nop 0
	global_load_lds_dwordx4 v240, s[48:49]
	s_waitcnt vmcnt(8)
	s_waitcnt lgkmcnt(0)
	s_setprio 1
	s_barrier
	v_mfma_f32_16x16x32_bf16 v[64:67], v[108:111], v[156:159], v[64:67]
	v_mfma_f32_16x16x32_bf16 v[64:67], v[120:123], v[160:163], v[64:67]
	v_mfma_f32_16x16x32_bf16 v[60:63], v[128:131], v[156:159], v[60:63]
	v_mfma_f32_16x16x32_bf16 v[60:63], v[132:135], v[160:163], v[60:63]
	v_mfma_f32_16x16x32_bf16 v[56:59], v[136:139], v[156:159], v[56:59]
	v_mfma_f32_16x16x32_bf16 v[56:59], v[144:147], v[160:163], v[56:59]
	v_mfma_f32_16x16x32_bf16 v[52:55], v[148:151], v[156:159], v[52:55]
	v_mfma_f32_16x16x32_bf16 v[52:55], v[152:155], v[160:163], v[52:55]
	v_mfma_f32_16x16x32_bf16 v[36:39], v[148:151], v[164:167], v[36:39]
	v_mfma_f32_16x16x32_bf16 v[36:39], v[152:155], v[176:179], v[36:39]
	v_mfma_f32_16x16x32_bf16 v[40:43], v[136:139], v[164:167], v[40:43]
	v_mfma_f32_16x16x32_bf16 v[40:43], v[144:147], v[176:179], v[40:43]
	v_mfma_f32_16x16x32_bf16 v[44:47], v[128:131], v[164:167], v[44:47]
	v_mfma_f32_16x16x32_bf16 v[44:47], v[132:135], v[176:179], v[44:47]
	v_mfma_f32_16x16x32_bf16 v[48:51], v[108:111], v[164:167], v[48:51]
	v_mfma_f32_16x16x32_bf16 v[48:51], v[120:123], v[176:179], v[48:51]
	v_mfma_f32_16x16x32_bf16 v[32:35], v[108:111], v[180:183], v[32:35]
	v_mfma_f32_16x16x32_bf16 v[32:35], v[120:123], v[184:187], v[32:35]
	v_mfma_f32_16x16x32_bf16 v[28:31], v[128:131], v[180:183], v[28:31]
	v_mfma_f32_16x16x32_bf16 v[28:31], v[132:135], v[184:187], v[28:31]
	v_mfma_f32_16x16x32_bf16 v[24:27], v[136:139], v[180:183], v[24:27]
	v_mfma_f32_16x16x32_bf16 v[24:27], v[144:147], v[184:187], v[24:27]
	v_mfma_f32_16x16x32_bf16 v[20:23], v[148:151], v[180:183], v[20:23]
	v_mfma_f32_16x16x32_bf16 v[20:23], v[152:155], v[184:187], v[20:23]
	v_mfma_f32_16x16x32_bf16 v[4:7], v[148:151], v[188:191], v[4:7]
	v_mfma_f32_16x16x32_bf16 v[4:7], v[152:155], v[202:205], v[4:7]
	v_mfma_f32_16x16x32_bf16 v[8:11], v[136:139], v[188:191], v[8:11]
	v_mfma_f32_16x16x32_bf16 v[8:11], v[144:147], v[202:205], v[8:11]
	v_mfma_f32_16x16x32_bf16 v[12:15], v[128:131], v[188:191], v[12:15]
	v_mfma_f32_16x16x32_bf16 v[12:15], v[132:135], v[202:205], v[12:15]
	v_mfma_f32_16x16x32_bf16 v[16:19], v[108:111], v[188:191], v[16:19]
	v_mfma_f32_16x16x32_bf16 v[16:19], v[120:123], v[202:205], v[16:19]
	s_barrier
	s_setprio 0
	s_add_u32 s4, s4, 0x100
	s_addc_u32 s5, s5, 0
	s_add_u32 s37, s37, 0x100
	s_addc_u32 s44, s44, 0
	s_cmp_ge_u32 s51, s43
	s_mov_b32 s45, s51
	.p2align 6

; #define PG8_STAGE(bufoff, gbase, voff) do { _Pragma("unroll") for (int _i = 0; _i < 2; ++_i) { \
;         const unsigned _m0 = ldsb + (unsigned)((bufoff) + _i * 8192); const char* _gb = (const char*)(gbase); \
;         asm volatile("s_mov_b32 m0, %0\n\ts_nop 0\n\tglobal_load_lds_dwordx4 %1, %2" :: "s"(_m0), "v"((voff)[_i]), "s"(_gb) : "m0", "memory"); } } while (0)
; #define PG8_LDA(dst, b, h) do { _Pragma("unroll") for (int m = 0; m < 4; ++m) _Pragma("unroll") for (int k = 0; k < 2; ++k) dst[m][k] = *(const LAS bf16x8*)(lds + PG8_SA(b, h) + aoff + m * 2048 + k * 1024); } while (0)
; #define PG8_LDB(dst, b, h) do { _Pragma("unroll") for (int n = 0; n < 2; ++n) _Pragma("unroll") for (int k = 0; k < 2; ++k) dst[n][k] = *(const LAS bf16x8*)(lds + PG8_SB(b, h) + boff + n * 2048 + k * 1024); } while (0)
; #define PG8_MMA(ai, bj, At, Bt) do { __builtin_amdgcn_s_setprio(1); _Pragma("unroll") for (int m = 0; m < 4; ++m) _Pragma("unroll") for (int n = 0; n < 2; ++n) _Pragma("unroll") for (int k = 0; k < 2; ++k) \
;         acc[ai][bj][m][n] = __builtin_amdgcn_mfma_f32_16x16x32_bf16(Bt[n][k], At[m][k], acc[ai][bj][m][n], 0, 0, 0); __builtin_amdgcn_s_setprio(0); } while (0)
; #define PG8_WAIT_V(n) asm volatile("s_waitcnt vmcnt(" #n ")" ::: "memory")
; #define PG8_WAIT_L(n) asm volatile("s_waitcnt lgkmcnt(" #n ")" ::: "memory")
; #define PG8_BAR __builtin_amdgcn_s_barrier()
; #define PG8_SCHED __builtin_amdgcn_sched_barrier(0)
; template <class Epi, bool ALIGN_EPI>
; __device__ __forceinline__ void gemm_phase(LAS unsigned char* lds, const Gemm g, const StaticOrder& S, const Epi& E) {
;     ...
;             PG8_LDB(B0, 0, 0); PG8_LDB(B1, 0, 1); PG8_SCHED; PG8_LDA(At, 0, 0); PG8_STAGE(PG8_SA(1, 1), a1 + hstepA, voffA);
;             PG8_WAIT_V(8); PG8_WAIT_L(0); PG8_BAR; PG8_MMA(0, 0, At, B0); PG8_MMA(0, 1, At, B1); PG8_BAR; PG8_SCHED;
;             PG8_LDA(At, 0, 1); PG8_STAGE(PG8_SB(0, 0), b2, voffB); PG8_STAGE(PG8_SB(0, 1), b2 + hstepB, voffB); PG8_STAGE(PG8_SA(0, 0), a2, voffA);
;             PG8_WAIT_V(8); PG8_WAIT_L(0); PG8_BAR; PG8_MMA(1, 0, At, B0); PG8_MMA(1, 1, At, B1); PG8_BAR; PG8_SCHED;
.LBB0_200:
	s_add_u32 s4, s48, 0x100
	s_addc_u32 s5, s49, 0
	s_add_u32 s15, s54, 0x100
	s_addc_u32 s42, s55, 0
	s_mov_b32 s43, 0
	s_add_i32 s44, s43, 2
	s_cmp_eq_u32 s68, s43
	s_cselect_b32 s56, s0, s15
	s_cselect_b32 s57, s1, s42
	s_cselect_b32 s54, s94, s4
	s_cselect_b32 s55, s95, s5
	s_add_u32 s48, s56, 0x80
	s_addc_u32 s49, s57, 0
	s_add_u32 s43, s15, s38
	s_addc_u32 s45, s42, 0
	s_add_u32 s58, s43, 0xffffff80
	s_addc_u32 s59, s45, -1
	s_mov_b32 m0, s37
	s_nop 0
	global_load_lds_dwordx4 v0, s[58:59]
	s_nop 0
	s_mov_b32 m0, s41
	s_nop 0
	global_load_lds_dwordx4 v206, s[58:59]
	s_waitcnt vmcnt(8)
	s_waitcnt lgkmcnt(0)
	s_setprio 1
	s_barrier
	v_mfma_f32_16x16x32_bf16 v[126:129], v[130:133], v[162:165], 0
	v_mfma_f32_16x16x32_bf16 v[126:129], v[134:137], v[166:169], v[126:129]
	v_mfma_f32_16x16x32_bf16 v[122:125], v[138:141], v[162:165], 0
	v_mfma_f32_16x16x32_bf16 v[122:125], v[142:145], v[166:169], v[122:125]
	v_mfma_f32_16x16x32_bf16 v[118:121], v[146:149], v[162:165], 0
	v_mfma_f32_16x16x32_bf16 v[118:121], v[150:153], v[166:169], v[118:121]
	v_mfma_f32_16x16x32_bf16 v[114:117], v[154:157], v[162:165], 0
	v_mfma_f32_16x16x32_bf16 v[114:117], v[158:161], v[166:169], v[114:117]
	v_mfma_f32_16x16x32_bf16 v[98:101], v[154:157], v[170:173], 0
	v_mfma_f32_16x16x32_bf16 v[98:101], v[158:161], v[174:177], v[98:101]
	v_mfma_f32_16x16x32_bf16 v[102:105], v[146:149], v[170:173], 0
	v_mfma_f32_16x16x32_bf16 v[102:105], v[150:153], v[174:177], v[102:105]
	v_mfma_f32_16x16x32_bf16 v[106:109], v[138:141], v[170:173], 0
	v_mfma_f32_16x16x32_bf16 v[106:109], v[142:145], v[174:177], v[106:109]
	v_mfma_f32_16x16x32_bf16 v[110:113], v[130:133], v[170:173], 0
	v_mfma_f32_16x16x32_bf16 v[110:113], v[134:137], v[174:177], v[110:113]
	v_mfma_f32_16x16x32_bf16 v[94:97], v[130:133], v[178:181], 0
	v_mfma_f32_16x16x32_bf16 v[94:97], v[134:137], v[182:185], v[94:97]
	v_mfma_f32_16x16x32_bf16 v[90:93], v[138:141], v[178:181], 0
	v_mfma_f32_16x16x32_bf16 v[90:93], v[142:145], v[182:185], v[90:93]
	v_mfma_f32_16x16x32_bf16 v[86:89], v[146:149], v[178:181], 0
	v_mfma_f32_16x16x32_bf16 v[86:89], v[150:153], v[182:185], v[86:89]
	v_mfma_f32_16x16x32_bf16 v[82:85], v[154:157], v[178:181], 0
	v_mfma_f32_16x16x32_bf16 v[82:85], v[158:161], v[182:185], v[82:85]
	v_mfma_f32_16x16x32_bf16 v[66:69], v[154:157], v[186:189], 0
	v_mfma_f32_16x16x32_bf16 v[66:69], v[158:161], v[190:193], v[66:69]
	v_mfma_f32_16x16x32_bf16 v[70:73], v[146:149], v[186:189], 0
	v_mfma_f32_16x16x32_bf16 v[70:73], v[150:153], v[190:193], v[70:73]
	v_mfma_f32_16x16x32_bf16 v[74:77], v[138:141], v[186:189], 0
	v_mfma_f32_16x16x32_bf16 v[74:77], v[142:145], v[190:193], v[74:77]
	v_mfma_f32_16x16x32_bf16 v[78:81], v[130:133], v[186:189], 0
	v_mfma_f32_16x16x32_bf16 v[78:81], v[134:137], v[190:193], v[78:81]
	s_barrier
	s_setprio 0
	ds_read_b128 v[162:165], v246 offset:16384
	ds_read_b128 v[166:169], v246 offset:17408
	ds_read_b128 v[170:173], v246 offset:18432
	ds_read_b128 v[174:177], v246 offset:19456
	ds_read_b128 v[178:181], v246 offset:20480
	ds_read_b128 v[182:185], v246 offset:21504
	ds_read_b128 v[186:189], v246 offset:22528
	ds_read_b128 v[190:193], v246 offset:23552
	s_mov_b32 m0, s46
	s_nop 0
	global_load_lds_dwordx4 v195, s[54:55]
	s_add_u32 s58, s54, s38
	s_mov_b32 m0, s26
	s_nop 0
	global_load_lds_dwordx4 v207, s[54:55]
	s_addc_u32 s59, s55, 0
	s_mov_b32 m0, s27
	s_nop 0
	global_load_lds_dwordx4 v195, s[58:59]
	s_nop 0
	s_mov_b32 m0, s30
	s_nop 0
	global_load_lds_dwordx4 v207, s[58:59]
	s_nop 0
	s_mov_b32 m0, s29
	s_nop 0
	global_load_lds_dwordx4 v0, s[56:57]
	s_nop 0
	s_mov_b32 m0, s17
	s_nop 0
	global_load_lds_dwordx4 v206, s[56:57]
	s_waitcnt vmcnt(8)
	s_waitcnt lgkmcnt(0)
	s_setprio 1
	s_barrier
	v_mfma_f32_16x16x32_bf16 v[62:65], v[130:133], v[162:165], 0
	v_mfma_f32_16x16x32_bf16 v[62:65], v[134:137], v[166:169], v[62:65]
	v_mfma_f32_16x16x32_bf16 v[58:61], v[138:141], v[162:165], 0
	v_mfma_f32_16x16x32_bf16 v[58:61], v[142:145], v[166:169], v[58:61]
	v_mfma_f32_16x16x32_bf16 v[54:57], v[146:149], v[162:165], 0
	v_mfma_f32_16x16x32_bf16 v[54:57], v[150:153], v[166:169], v[54:57]
	v_mfma_f32_16x16x32_bf16 v[50:53], v[154:157], v[162:165], 0
	v_mfma_f32_16x16x32_bf16 v[50:53], v[158:161], v[166:169], v[50:53]
	v_mfma_f32_16x16x32_bf16 v[34:37], v[154:157], v[170:173], 0
	v_mfma_f32_16x16x32_bf16 v[34:37], v[158:161], v[174:177], v[34:37]
	v_mfma_f32_16x16x32_bf16 v[38:41], v[146:149], v[170:173], 0
	v_mfma_f32_16x16x32_bf16 v[38:41], v[150:153], v[174:177], v[38:41]
	v_mfma_f32_16x16x32_bf16 v[42:45], v[138:141], v[170:173], 0
	v_mfma_f32_16x16x32_bf16 v[42:45], v[142:145], v[174:177], v[42:45]
	v_mfma_f32_16x16x32_bf16 v[46:49], v[130:133], v[170:173], 0
	v_mfma_f32_16x16x32_bf16 v[46:49], v[134:137], v[174:177], v[46:49]
	v_mfma_f32_16x16x32_bf16 v[30:33], v[130:133], v[178:181], 0
	v_mfma_f32_16x16x32_bf16 v[30:33], v[134:137], v[182:185], v[30:33]
	v_mfma_f32_16x16x32_bf16 v[26:29], v[138:141], v[178:181], 0
	v_mfma_f32_16x16x32_bf16 v[26:29], v[142:145], v[182:185], v[26:29]
	v_mfma_f32_16x16x32_bf16 v[22:25], v[146:149], v[178:181], 0
	v_mfma_f32_16x16x32_bf16 v[22:25], v[150:153], v[182:185], v[22:25]
	v_mfma_f32_16x16x32_bf16 v[18:21], v[154:157], v[178:181], 0
	v_mfma_f32_16x16x32_bf16 v[18:21], v[158:161], v[182:185], v[18:21]
	v_mfma_f32_16x16x32_bf16 v[2:5], v[154:157], v[186:189], 0
	v_mfma_f32_16x16x32_bf16 v[2:5], v[158:161], v[190:193], v[2:5]
	v_mfma_f32_16x16x32_bf16 v[6:9], v[146:149], v[186:189], 0
	v_mfma_f32_16x16x32_bf16 v[6:9], v[150:153], v[190:193], v[6:9]
	v_mfma_f32_16x16x32_bf16 v[10:13], v[138:141], v[186:189], 0
	v_mfma_f32_16x16x32_bf16 v[10:13], v[142:145], v[190:193], v[10:13]
	v_mfma_f32_16x16x32_bf16 v[14:17], v[130:133], v[186:189], 0
	v_mfma_f32_16x16x32_bf16 v[14:17], v[134:137], v[190:193], v[14:17]
	s_barrier
; #define PG8_STAGE(bufoff, gbase, voff) do { _Pragma("unroll") for (int _i = 0; _i < 2; ++_i) { \
;         const unsigned _m0 = ldsb + (unsigned)((bufoff) + _i * 8192); const char* _gb = (const char*)(gbase); \
;         asm volatile("s_mov_b32 m0, %0\n\ts_nop 0\n\tglobal_load_lds_dwordx4 %1, %2" :: "s"(_m0), "v"((voff)[_i]), "s"(_gb) : "m0", "memory"); } } while (0)
; #define PG8_LDA(dst, b, h) do { _Pragma("unroll") for (int m = 0; m < 4; ++m) _Pragma("unroll") for (int k = 0; k < 2; ++k) dst[m][k] = *(const LAS bf16x8*)(lds + PG8_SA(b, h) + aoff + m * 2048 + k * 1024); } while (0)
; #define PG8_LDB(dst, b, h) do { _Pragma("unroll") for (int n = 0; n < 2; ++n) _Pragma("unroll") for (int k = 0; k < 2; ++k) dst[n][k] = *(const LAS bf16x8*)(lds + PG8_SB(b, h) + boff + n * 2048 + k * 1024); } while (0)
; #define PG8_MMA(ai, bj, At, Bt) do { __builtin_amdgcn_s_setprio(1); _Pragma("unroll") for (int m = 0; m < 4; ++m) _Pragma("unroll") for (int n = 0; n < 2; ++n) _Pragma("unroll") for (int k = 0; k < 2; ++k) \
;         acc[ai][bj][m][n] = __builtin_amdgcn_mfma_f32_16x16x32_bf16(Bt[n][k], At[m][k], acc[ai][bj][m][n], 0, 0, 0); __builtin_amdgcn_s_setprio(0); } while (0)
; #define PG8_WAIT_V(n) asm volatile("s_waitcnt vmcnt(" #n ")" ::: "memory")
; #define PG8_WAIT_L(n) asm volatile("s_waitcnt lgkmcnt(" #n ")" ::: "memory")
; #define PG8_BAR __builtin_amdgcn_s_barrier()
; #define PG8_SCHED __builtin_amdgcn_sched_barrier(0)
; template <class Epi, bool ALIGN_EPI>
; __device__ __forceinline__ void gemm_phase(LAS unsigned char* lds, const Gemm g, const StaticOrder& S, const Epi& E) {
;     ...
;             PG8_LDB(B0, 1, 0); PG8_LDB(B1, 1, 1); PG8_SCHED; PG8_LDA(At, 1, 0); PG8_STAGE(PG8_SA(0, 1), a2 + hstepA, voffA);
;             PG8_WAIT_V(8); PG8_WAIT_L(0); PG8_BAR; PG8_MMA(0, 0, At, B0); PG8_MMA(0, 1, At, B1); PG8_BAR; PG8_SCHED;
;             PG8_LDA(At, 1, 1); PG8_STAGE(PG8_SB(1, 0), b3, voffB); PG8_STAGE(PG8_SB(1, 1), b3 + hstepB, voffB); PG8_STAGE(PG8_SA(1, 0), a3, voffA);
;             PG8_WAIT_V(8); PG8_WAIT_L(0); PG8_BAR; PG8_MMA(1, 0, At, B0); PG8_MMA(1, 1, At, B1); PG8_BAR; PG8_SCHED;
;         }
	s_setprio 0
	v_add_u32_e32 v142, 0x18000, v245
	v_add_u32_e32 v158, 0x1c000, v245
	ds_read_b128 v[130:133], v142
	ds_read_b128 v[134:137], v142 offset:1024
	ds_read_b128 v[138:141], v142 offset:2048
	ds_read_b128 v[142:145], v142 offset:3072
	ds_read_b128 v[146:149], v158
	ds_read_b128 v[150:153], v158 offset:1024
	ds_read_b128 v[154:157], v158 offset:2048
	ds_read_b128 v[158:161], v158 offset:3072
	ds_read_b128 v[162:165], v246 offset:32768
	ds_read_b128 v[166:169], v246 offset:33792
	ds_read_b128 v[170:173], v246 offset:34816
	ds_read_b128 v[174:177], v246 offset:35840
	ds_read_b128 v[178:181], v246 offset:36864
	ds_read_b128 v[182:185], v246 offset:37888
	ds_read_b128 v[186:189], v246 offset:38912
	ds_read_b128 v[190:193], v246 offset:39936
	s_add_u32 s56, s56, s38
	s_addc_u32 s57, s57, 0
	s_mov_b32 m0, s31
	s_nop 0
	global_load_lds_dwordx4 v0, s[56:57]
	s_nop 0
	s_mov_b32 m0, s53
	s_nop 0
	global_load_lds_dwordx4 v206, s[56:57]
	s_waitcnt vmcnt(8)
	s_waitcnt lgkmcnt(0)
	s_setprio 1
	s_barrier
	v_mfma_f32_16x16x32_bf16 v[126:129], v[130:133], v[162:165], v[126:129]
	v_mfma_f32_16x16x32_bf16 v[126:129], v[134:137], v[166:169], v[126:129]
	v_mfma_f32_16x16x32_bf16 v[122:125], v[138:141], v[162:165], v[122:125]
	v_mfma_f32_16x16x32_bf16 v[122:125], v[142:145], v[166:169], v[122:125]
	v_mfma_f32_16x16x32_bf16 v[118:121], v[146:149], v[162:165], v[118:121]
	v_mfma_f32_16x16x32_bf16 v[118:121], v[150:153], v[166:169], v[118:121]
	v_mfma_f32_16x16x32_bf16 v[114:117], v[154:157], v[162:165], v[114:117]
	v_mfma_f32_16x16x32_bf16 v[114:117], v[158:161], v[166:169], v[114:117]
	v_mfma_f32_16x16x32_bf16 v[98:101], v[154:157], v[170:173], v[98:101]
	v_mfma_f32_16x16x32_bf16 v[98:101], v[158:161], v[174:177], v[98:101]
	v_mfma_f32_16x16x32_bf16 v[102:105], v[146:149], v[170:173], v[102:105]
	v_mfma_f32_16x16x32_bf16 v[102:105], v[150:153], v[174:177], v[102:105]
	v_mfma_f32_16x16x32_bf16 v[106:109], v[138:141], v[170:173], v[106:109]
	v_mfma_f32_16x16x32_bf16 v[106:109], v[142:145], v[174:177], v[106:109]
	v_mfma_f32_16x16x32_bf16 v[110:113], v[130:133], v[170:173], v[110:113]
	v_mfma_f32_16x16x32_bf16 v[110:113], v[134:137], v[174:177], v[110:113]
	v_mfma_f32_16x16x32_bf16 v[94:97], v[130:133], v[178:181], v[94:97]
	v_mfma_f32_16x16x32_bf16 v[94:97], v[134:137], v[182:185], v[94:97]
	v_mfma_f32_16x16x32_bf16 v[90:93], v[138:141], v[178:181], v[90:93]
	v_mfma_f32_16x16x32_bf16 v[90:93], v[142:145], v[182:185], v[90:93]
	v_mfma_f32_16x16x32_bf16 v[86:89], v[146:149], v[178:181], v[86:89]
	v_mfma_f32_16x16x32_bf16 v[86:89], v[150:153], v[182:185], v[86:89]
	v_mfma_f32_16x16x32_bf16 v[82:85], v[154:157], v[178:181], v[82:85]
	v_mfma_f32_16x16x32_bf16 v[82:85], v[158:161], v[182:185], v[82:85]
	v_mfma_f32_16x16x32_bf16 v[66:69], v[154:157], v[186:189], v[66:69]
	v_mfma_f32_16x16x32_bf16 v[66:69], v[158:161], v[190:193], v[66:69]
	v_mfma_f32_16x16x32_bf16 v[70:73], v[146:149], v[186:189], v[70:73]
	v_mfma_f32_16x16x32_bf16 v[70:73], v[150:153], v[190:193], v[70:73]
	v_mfma_f32_16x16x32_bf16 v[74:77], v[138:141], v[186:189], v[74:77]
	v_mfma_f32_16x16x32_bf16 v[74:77], v[142:145], v[190:193], v[74:77]
	v_mfma_f32_16x16x32_bf16 v[78:81], v[130:133], v[186:189], v[78:81]
	v_mfma_f32_16x16x32_bf16 v[78:81], v[134:137], v[190:193], v[78:81]
	s_barrier
	s_setprio 0
	ds_read_b128 v[162:165], v246 offset:49152
	ds_read_b128 v[166:169], v246 offset:50176
	ds_read_b128 v[170:173], v246 offset:51200
	ds_read_b128 v[174:177], v246 offset:52224
	ds_read_b128 v[178:181], v246 offset:53248
	ds_read_b128 v[182:185], v246 offset:54272
	ds_read_b128 v[186:189], v246 offset:55296
	ds_read_b128 v[190:193], v246 offset:56320
	s_add_u32 s54, s54, 0x80
	s_addc_u32 s55, s55, 0
	s_mov_b32 m0, s85
	s_nop 0
	global_load_lds_dwordx4 v195, s[54:55]
	s_nop 0
	s_mov_b32 m0, s65
	s_nop 0
	global_load_lds_dwordx4 v207, s[54:55]
	s_add_u32 s54, s58, 0x80
	s_addc_u32 s55, s59, 0
	s_mov_b32 m0, s93
	s_nop 0
	global_load_lds_dwordx4 v195, s[54:55]
	s_nop 0
	s_mov_b32 m0, s28
	s_nop 0
	global_load_lds_dwordx4 v207, s[54:55]
	s_nop 0
	s_mov_b32 m0, s67
	s_nop 0
	global_load_lds_dwordx4 v0, s[48:49]
	s_nop 0
	s_mov_b32 m0, s92
	s_nop 0
	global_load_lds_dwordx4 v206, s[48:49]
	s_waitcnt vmcnt(8)
	s_waitcnt lgkmcnt(0)
	s_setprio 1
	s_barrier
	v_mfma_f32_16x16x32_bf16 v[62:65], v[130:133], v[162:165], v[62:65]
	v_mfma_f32_16x16x32_bf16 v[62:65], v[134:137], v[166:169], v[62:65]
	v_mfma_f32_16x16x32_bf16 v[58:61], v[138:141], v[162:165], v[58:61]
	v_mfma_f32_16x16x32_bf16 v[58:61], v[142:145], v[166:169], v[58:61]
	v_mfma_f32_16x16x32_bf16 v[54:57], v[146:149], v[162:165], v[54:57]
	v_mfma_f32_16x16x32_bf16 v[54:57], v[150:153], v[166:169], v[54:57]
	v_mfma_f32_16x16x32_bf16 v[50:53], v[154:157], v[162:165], v[50:53]
	v_mfma_f32_16x16x32_bf16 v[50:53], v[158:161], v[166:169], v[50:53]
	v_mfma_f32_16x16x32_bf16 v[34:37], v[154:157], v[170:173], v[34:37]
	v_mfma_f32_16x16x32_bf16 v[34:37], v[158:161], v[174:177], v[34:37]
	v_mfma_f32_16x16x32_bf16 v[38:41], v[146:149], v[170:173], v[38:41]
	v_mfma_f32_16x16x32_bf16 v[38:41], v[150:153], v[174:177], v[38:41]
	v_mfma_f32_16x16x32_bf16 v[42:45], v[138:141], v[170:173], v[42:45]
	v_mfma_f32_16x16x32_bf16 v[42:45], v[142:145], v[174:177], v[42:45]
	v_mfma_f32_16x16x32_bf16 v[46:49], v[130:133], v[170:173], v[46:49]
	v_mfma_f32_16x16x32_bf16 v[46:49], v[134:137], v[174:177], v[46:49]
	v_mfma_f32_16x16x32_bf16 v[30:33], v[130:133], v[178:181], v[30:33]
	v_mfma_f32_16x16x32_bf16 v[30:33], v[134:137], v[182:185], v[30:33]
	v_mfma_f32_16x16x32_bf16 v[26:29], v[138:141], v[178:181], v[26:29]
	v_mfma_f32_16x16x32_bf16 v[26:29], v[142:145], v[182:185], v[26:29]
	v_mfma_f32_16x16x32_bf16 v[22:25], v[146:149], v[178:181], v[22:25]
	v_mfma_f32_16x16x32_bf16 v[22:25], v[150:153], v[182:185], v[22:25]
	v_mfma_f32_16x16x32_bf16 v[18:21], v[154:157], v[178:181], v[18:21]
	v_mfma_f32_16x16x32_bf16 v[18:21], v[158:161], v[182:185], v[18:21]
	v_mfma_f32_16x16x32_bf16 v[2:5], v[154:157], v[186:189], v[2:5]
	v_mfma_f32_16x16x32_bf16 v[2:5], v[158:161], v[190:193], v[2:5]
	v_mfma_f32_16x16x32_bf16 v[6:9], v[146:149], v[186:189], v[6:9]
	v_mfma_f32_16x16x32_bf16 v[6:9], v[150:153], v[190:193], v[6:9]
	v_mfma_f32_16x16x32_bf16 v[10:13], v[138:141], v[186:189], v[10:13]
	v_mfma_f32_16x16x32_bf16 v[10:13], v[142:145], v[190:193], v[10:13]
	v_mfma_f32_16x16x32_bf16 v[14:17], v[130:133], v[186:189], v[14:17]
	v_mfma_f32_16x16x32_bf16 v[14:17], v[134:137], v[190:193], v[14:17]
	s_barrier
	s_setprio 0
	s_add_u32 s4, s4, 0x100
	s_addc_u32 s5, s5, 0
	s_add_u32 s15, s15, 0x100
	s_addc_u32 s42, s42, 0
	s_cmp_ge_u32 s44, s36
	s_mov_b32 s43, s44
	.p2align 6

; #define PG8_STAGE(bufoff, gbase, voff) do { _Pragma("unroll") for (int _i = 0; _i < 2; ++_i) { \
;         const unsigned _m0 = ldsb + (unsigned)((bufoff) + _i * 8192); const char* _gb = (const char*)(gbase); \
;         asm volatile("s_mov_b32 m0, %0\n\ts_nop 0\n\tglobal_load_lds_dwordx4 %1, %2" :: "s"(_m0), "v"((voff)[_i]), "s"(_gb) : "m0", "memory"); } } while (0)
; #define PG8_LDA(dst, b, h) do { _Pragma("unroll") for (int m = 0; m < 4; ++m) _Pragma("unroll") for (int k = 0; k < 2; ++k) dst[m][k] = *(const LAS bf16x8*)(lds + PG8_SA(b, h) + aoff + m * 2048 + k * 1024); } while (0)
; #define PG8_LDB(dst, b, h) do { _Pragma("unroll") for (int n = 0; n < 2; ++n) _Pragma("unroll") for (int k = 0; k < 2; ++k) dst[n][k] = *(const LAS bf16x8*)(lds + PG8_SB(b, h) + boff + n * 2048 + k * 1024); } while (0)
; #define PG8_WAIT_V(n) asm volatile("s_waitcnt vmcnt(" #n ")" ::: "memory")
; #define PG8_WAIT_L(n) asm volatile("s_waitcnt lgkmcnt(" #n ")" ::: "memory")
; #define PG8_BAR __builtin_amdgcn_s_barrier()
; #define PG8_SCHED __builtin_amdgcn_sched_barrier(0)
; template <class Epi, bool ALIGN_EPI>
; __device__ __forceinline__ void gemm_phase(LAS unsigned char* lds, const Gemm g, const StaticOrder& S, const Epi& E) {
;     ...
;         const char* nA = has_next ? (const char*)g.A + (size_t)nxt.pm * tstepA + (size_t)nxt.pn * g.a_pn_off * 2 + (size_t)(nxt.pm >> 4) * g.a_adj : cA; const char* nB = has_next ? (const char*)g.Bt + (size_t)nxt.pn * tstepB : cB;
;         for (int t = 0; t < nt; t += 2) {
;             const bool last = (t == nt - 2);
;             const char* a1 = cA + (size_t)(t + 1) * kstep;
;             const char* a2 = last ? nA : cA + (size_t)(t + 2) * kstep; const char* b2 = last ? nB : cB + (size_t)(t + 2) * kstep;
;             const char* a3 = a2 + kstep; const char* b3 = b2 + kstep;
;             PG8_LDB(B0, 0, 0); PG8_LDB(B1, 0, 1); PG8_SCHED; PG8_LDA(At, 0, 0); PG8_STAGE(PG8_SA(1, 1), a1 + hstepA, voffA);
;             PG8_WAIT_V(8); PG8_WAIT_L(0); PG8_BAR; PG8_MMA(0, 0, At, B0); PG8_MMA(0, 1, At, B1); PG8_BAR; PG8_SCHED;
;             PG8_LDA(At, 0, 1); PG8_STAGE(PG8_SB(0, 0), b2, voffB); PG8_STAGE(PG8_SB(0, 1), b2 + hstepB, voffB); PG8_STAGE(PG8_SA(0, 0), a2, voffA);
;             PG8_WAIT_V(8); PG8_WAIT_L(0); PG8_BAR; PG8_MMA(1, 0, At, B0); PG8_MMA(1, 1, At, B1); PG8_BAR; PG8_SCHED;
.LBB0_270:
	s_add_u32 s4, s56, 0x100
	s_addc_u32 s5, s57, 0
	s_add_u32 s0, s58, 0x40080
	s_addc_u32 s1, s59, 0
	s_mov_b32 s44, 0
	s_add_i32 s55, s44, 2
	s_add_u32 s45, s0, 0xfffc0080
	s_addc_u32 s56, s1, -1
	s_cmp_eq_u32 s68, s44
	s_cselect_b32 s60, s96, s45
	s_cselect_b32 s61, s97, s56
	s_cselect_b32 s58, s48, s4
	s_cselect_b32 s59, s49, s5
	s_add_u32 s56, s60, 0x80
	s_addc_u32 s57, s61, 0
	s_mov_b32 m0, s41
	s_nop 0
	global_load_lds_dwordx4 v165, s[0:1]
	s_nop 0
	s_mov_b32 m0, s30
	s_nop 0
	global_load_lds_dwordx4 v171, s[0:1]
	s_waitcnt vmcnt(8)
	s_waitcnt lgkmcnt(0)
	s_setprio 1
	s_barrier
	v_mfma_f32_16x16x32_bf16 v[126:129], v[130:133], v[182:185], 0
	v_mfma_f32_16x16x32_bf16 v[126:129], v[134:137], v[186:189], v[126:129]
	v_mfma_f32_16x16x32_bf16 v[122:125], v[138:141], v[182:185], 0
	v_mfma_f32_16x16x32_bf16 v[122:125], v[142:145], v[186:189], v[122:125]
	v_mfma_f32_16x16x32_bf16 v[118:121], v[146:149], v[182:185], 0
	v_mfma_f32_16x16x32_bf16 v[118:121], v[150:153], v[186:189], v[118:121]
	v_mfma_f32_16x16x32_bf16 v[110:113], v[154:157], v[182:185], 0
	v_mfma_f32_16x16x32_bf16 v[110:113], v[158:161], v[186:189], v[110:113]
	v_mfma_f32_16x16x32_bf16 v[94:97], v[154:157], v[190:193], 0
	v_mfma_f32_16x16x32_bf16 v[94:97], v[158:161], v[202:205], v[94:97]
	v_mfma_f32_16x16x32_bf16 v[102:105], v[146:149], v[190:193], 0
	v_mfma_f32_16x16x32_bf16 v[102:105], v[150:153], v[202:205], v[102:105]
	v_mfma_f32_16x16x32_bf16 v[106:109], v[138:141], v[190:193], 0
	v_mfma_f32_16x16x32_bf16 v[106:109], v[142:145], v[202:205], v[106:109]
	v_mfma_f32_16x16x32_bf16 v[114:117], v[130:133], v[190:193], 0
	v_mfma_f32_16x16x32_bf16 v[114:117], v[134:137], v[202:205], v[114:117]
	v_mfma_f32_16x16x32_bf16 v[98:101], v[130:133], v[206:209], 0
	v_mfma_f32_16x16x32_bf16 v[98:101], v[134:137], v[210:213], v[98:101]
	v_mfma_f32_16x16x32_bf16 v[90:93], v[138:141], v[206:209], 0
	v_mfma_f32_16x16x32_bf16 v[90:93], v[142:145], v[210:213], v[90:93]
	v_mfma_f32_16x16x32_bf16 v[86:89], v[146:149], v[206:209], 0
	v_mfma_f32_16x16x32_bf16 v[86:89], v[150:153], v[210:213], v[86:89]
	v_mfma_f32_16x16x32_bf16 v[78:81], v[154:157], v[206:209], 0
	v_mfma_f32_16x16x32_bf16 v[78:81], v[158:161], v[210:213], v[78:81]
	v_mfma_f32_16x16x32_bf16 v[66:69], v[154:157], v[214:217], 0
	v_mfma_f32_16x16x32_bf16 v[66:69], v[158:161], v[240:243], v[66:69]
	v_mfma_f32_16x16x32_bf16 v[70:73], v[146:149], v[214:217], 0
	v_mfma_f32_16x16x32_bf16 v[70:73], v[150:153], v[240:243], v[70:73]
	v_mfma_f32_16x16x32_bf16 v[74:77], v[138:141], v[214:217], 0
	v_mfma_f32_16x16x32_bf16 v[74:77], v[142:145], v[240:243], v[74:77]
	v_mfma_f32_16x16x32_bf16 v[82:85], v[130:133], v[214:217], 0
	v_mfma_f32_16x16x32_bf16 v[82:85], v[134:137], v[240:243], v[82:85]
	s_barrier
	s_setprio 0
	ds_read_b128 v[182:185], v180 offset:16384
	ds_read_b128 v[186:189], v180 offset:17408
	ds_read_b128 v[190:193], v180 offset:18432
	ds_read_b128 v[202:205], v180 offset:19456
	ds_read_b128 v[206:209], v180 offset:20480
	ds_read_b128 v[210:213], v180 offset:21504
	ds_read_b128 v[214:217], v180 offset:22528
	ds_read_b128 v[240:243], v180 offset:23552
	s_mov_b32 m0, s42
	s_nop 0
	global_load_lds_dwordx4 v167, s[58:59]
	s_add_u32 s44, s58, s14
	s_mov_b32 m0, s43
	s_nop 0
	global_load_lds_dwordx4 v175, s[58:59]
	s_addc_u32 s45, s59, 0
	s_mov_b32 m0, s46
	s_nop 0
	global_load_lds_dwordx4 v167, s[44:45]
	s_nop 0
	s_mov_b32 m0, s50
	s_nop 0
	global_load_lds_dwordx4 v175, s[44:45]
	s_nop 0
	s_mov_b32 m0, s17
	s_nop 0
	global_load_lds_dwordx4 v165, s[60:61]
	s_nop 0
	s_mov_b32 m0, s53
	s_nop 0
	global_load_lds_dwordx4 v171, s[60:61]
	s_waitcnt vmcnt(8)
	s_waitcnt lgkmcnt(0)
	s_setprio 1
	s_barrier
	v_mfma_f32_16x16x32_bf16 v[62:65], v[130:133], v[182:185], 0
	v_mfma_f32_16x16x32_bf16 v[62:65], v[134:137], v[186:189], v[62:65]
	v_mfma_f32_16x16x32_bf16 v[58:61], v[138:141], v[182:185], 0
	v_mfma_f32_16x16x32_bf16 v[58:61], v[142:145], v[186:189], v[58:61]
	v_mfma_f32_16x16x32_bf16 v[54:57], v[146:149], v[182:185], 0
	v_mfma_f32_16x16x32_bf16 v[54:57], v[150:153], v[186:189], v[54:57]
	v_mfma_f32_16x16x32_bf16 v[50:53], v[154:157], v[182:185], 0
	v_mfma_f32_16x16x32_bf16 v[50:53], v[158:161], v[186:189], v[50:53]
	v_mfma_f32_16x16x32_bf16 v[30:33], v[154:157], v[190:193], 0
	v_mfma_f32_16x16x32_bf16 v[30:33], v[158:161], v[202:205], v[30:33]
	v_mfma_f32_16x16x32_bf16 v[38:41], v[146:149], v[190:193], 0
	v_mfma_f32_16x16x32_bf16 v[38:41], v[150:153], v[202:205], v[38:41]
	v_mfma_f32_16x16x32_bf16 v[42:45], v[138:141], v[190:193], 0
	v_mfma_f32_16x16x32_bf16 v[42:45], v[142:145], v[202:205], v[42:45]
	v_mfma_f32_16x16x32_bf16 v[46:49], v[130:133], v[190:193], 0
	v_mfma_f32_16x16x32_bf16 v[46:49], v[134:137], v[202:205], v[46:49]
	v_mfma_f32_16x16x32_bf16 v[34:37], v[130:133], v[206:209], 0
	v_mfma_f32_16x16x32_bf16 v[34:37], v[134:137], v[210:213], v[34:37]
	v_mfma_f32_16x16x32_bf16 v[26:29], v[138:141], v[206:209], 0
	v_mfma_f32_16x16x32_bf16 v[26:29], v[142:145], v[210:213], v[26:29]
	v_mfma_f32_16x16x32_bf16 v[22:25], v[146:149], v[206:209], 0
	v_mfma_f32_16x16x32_bf16 v[22:25], v[150:153], v[210:213], v[22:25]
	v_mfma_f32_16x16x32_bf16 v[14:17], v[154:157], v[206:209], 0
	v_mfma_f32_16x16x32_bf16 v[14:17], v[158:161], v[210:213], v[14:17]
	v_mfma_f32_16x16x32_bf16 v[2:5], v[154:157], v[214:217], 0
	v_mfma_f32_16x16x32_bf16 v[2:5], v[158:161], v[240:243], v[2:5]
	v_mfma_f32_16x16x32_bf16 v[6:9], v[146:149], v[214:217], 0
	v_mfma_f32_16x16x32_bf16 v[6:9], v[150:153], v[240:243], v[6:9]
	v_mfma_f32_16x16x32_bf16 v[10:13], v[138:141], v[214:217], 0
	v_mfma_f32_16x16x32_bf16 v[10:13], v[142:145], v[240:243], v[10:13]
	v_mfma_f32_16x16x32_bf16 v[18:21], v[130:133], v[214:217], 0
	v_mfma_f32_16x16x32_bf16 v[18:21], v[134:137], v[240:243], v[18:21]
	s_barrier
; #define PG8_STAGE(bufoff, gbase, voff) do { _Pragma("unroll") for (int _i = 0; _i < 2; ++_i) { \
;         const unsigned _m0 = ldsb + (unsigned)((bufoff) + _i * 8192); const char* _gb = (const char*)(gbase); \
;         asm volatile("s_mov_b32 m0, %0\n\ts_nop 0\n\tglobal_load_lds_dwordx4 %1, %2" :: "s"(_m0), "v"((voff)[_i]), "s"(_gb) : "m0", "memory"); } } while (0)
; #define PG8_LDA(dst, b, h) do { _Pragma("unroll") for (int m = 0; m < 4; ++m) _Pragma("unroll") for (int k = 0; k < 2; ++k) dst[m][k] = *(const LAS bf16x8*)(lds + PG8_SA(b, h) + aoff + m * 2048 + k * 1024); } while (0)
; #define PG8_LDB(dst, b, h) do { _Pragma("unroll") for (int n = 0; n < 2; ++n) _Pragma("unroll") for (int k = 0; k < 2; ++k) dst[n][k] = *(const LAS bf16x8*)(lds + PG8_SB(b, h) + boff + n * 2048 + k * 1024); } while (0)
; #define PG8_MMA(ai, bj, At, Bt) do { __builtin_amdgcn_s_setprio(1); _Pragma("unroll") for (int m = 0; m < 4; ++m) _Pragma("unroll") for (int n = 0; n < 2; ++n) _Pragma("unroll") for (int k = 0; k < 2; ++k) \
;         acc[ai][bj][m][n] = __builtin_amdgcn_mfma_f32_16x16x32_bf16(Bt[n][k], At[m][k], acc[ai][bj][m][n], 0, 0, 0); __builtin_amdgcn_s_setprio(0); } while (0)
; #define PG8_WAIT_V(n) asm volatile("s_waitcnt vmcnt(" #n ")" ::: "memory")
; #define PG8_WAIT_L(n) asm volatile("s_waitcnt lgkmcnt(" #n ")" ::: "memory")
; #define PG8_BAR __builtin_amdgcn_s_barrier()
; #define PG8_SCHED __builtin_amdgcn_sched_barrier(0)
; template <class Epi, bool ALIGN_EPI>
; __device__ __forceinline__ void gemm_phase(LAS unsigned char* lds, const Gemm g, const StaticOrder& S, const Epi& E) {
;     ...
;             PG8_LDB(B0, 1, 0); PG8_LDB(B1, 1, 1); PG8_SCHED; PG8_LDA(At, 1, 0); PG8_STAGE(PG8_SA(0, 1), a2 + hstepA, voffA);
;             PG8_WAIT_V(8); PG8_WAIT_L(0); PG8_BAR; PG8_MMA(0, 0, At, B0); PG8_MMA(0, 1, At, B1); PG8_BAR; PG8_SCHED;
;             PG8_LDA(At, 1, 1); PG8_STAGE(PG8_SB(1, 0), b3, voffB); PG8_STAGE(PG8_SB(1, 1), b3 + hstepB, voffB); PG8_STAGE(PG8_SA(1, 0), a3, voffA);
;             PG8_WAIT_V(8); PG8_WAIT_L(0); PG8_BAR; PG8_MMA(1, 0, At, B0); PG8_MMA(1, 1, At, B1); PG8_BAR; PG8_SCHED;
;         }
	s_setprio 0
	v_add_u32_e32 v0, 0x18000, v179
	ds_read_b128 v[130:133], v0
	ds_read_b128 v[134:137], v0 offset:1024
	ds_read_b128 v[138:141], v0 offset:2048
	ds_read_b128 v[142:145], v0 offset:3072
	v_add_u32_e32 v0, 0x1c000, v179
	ds_read_b128 v[146:149], v0
	ds_read_b128 v[150:153], v0 offset:1024
	ds_read_b128 v[154:157], v0 offset:2048
	ds_read_b128 v[158:161], v0 offset:3072
	ds_read_b128 v[182:185], v180 offset:32768
	ds_read_b128 v[186:189], v180 offset:33792
	ds_read_b128 v[190:193], v180 offset:34816
	ds_read_b128 v[202:205], v180 offset:35840
	ds_read_b128 v[206:209], v180 offset:36864
	ds_read_b128 v[210:213], v180 offset:37888
	ds_read_b128 v[214:217], v180 offset:38912
	ds_read_b128 v[240:243], v180 offset:39936
	s_add_u32 s60, s60, 0x40000
	s_addc_u32 s61, s61, 0
	s_mov_b32 m0, s65
	s_nop 0
	global_load_lds_dwordx4 v165, s[60:61]
	s_nop 0
	s_mov_b32 m0, s67
	s_nop 0
	global_load_lds_dwordx4 v171, s[60:61]
	s_waitcnt vmcnt(8)
	s_waitcnt lgkmcnt(0)
	s_setprio 1
	s_barrier
	v_mfma_f32_16x16x32_bf16 v[126:129], v[130:133], v[182:185], v[126:129]
	v_mfma_f32_16x16x32_bf16 v[126:129], v[134:137], v[186:189], v[126:129]
	v_mfma_f32_16x16x32_bf16 v[122:125], v[138:141], v[182:185], v[122:125]
	v_mfma_f32_16x16x32_bf16 v[122:125], v[142:145], v[186:189], v[122:125]
	v_mfma_f32_16x16x32_bf16 v[118:121], v[146:149], v[182:185], v[118:121]
	v_mfma_f32_16x16x32_bf16 v[118:121], v[150:153], v[186:189], v[118:121]
	v_mfma_f32_16x16x32_bf16 v[110:113], v[154:157], v[182:185], v[110:113]
	v_mfma_f32_16x16x32_bf16 v[110:113], v[158:161], v[186:189], v[110:113]
	v_mfma_f32_16x16x32_bf16 v[94:97], v[154:157], v[190:193], v[94:97]
	v_mfma_f32_16x16x32_bf16 v[94:97], v[158:161], v[202:205], v[94:97]
	v_mfma_f32_16x16x32_bf16 v[102:105], v[146:149], v[190:193], v[102:105]
	v_mfma_f32_16x16x32_bf16 v[102:105], v[150:153], v[202:205], v[102:105]
	v_mfma_f32_16x16x32_bf16 v[106:109], v[138:141], v[190:193], v[106:109]
	v_mfma_f32_16x16x32_bf16 v[106:109], v[142:145], v[202:205], v[106:109]
	v_mfma_f32_16x16x32_bf16 v[114:117], v[130:133], v[190:193], v[114:117]
	v_mfma_f32_16x16x32_bf16 v[114:117], v[134:137], v[202:205], v[114:117]
	v_mfma_f32_16x16x32_bf16 v[98:101], v[130:133], v[206:209], v[98:101]
	v_mfma_f32_16x16x32_bf16 v[98:101], v[134:137], v[210:213], v[98:101]
	v_mfma_f32_16x16x32_bf16 v[90:93], v[138:141], v[206:209], v[90:93]
	v_mfma_f32_16x16x32_bf16 v[90:93], v[142:145], v[210:213], v[90:93]
	v_mfma_f32_16x16x32_bf16 v[86:89], v[146:149], v[206:209], v[86:89]
	v_mfma_f32_16x16x32_bf16 v[86:89], v[150:153], v[210:213], v[86:89]
	v_mfma_f32_16x16x32_bf16 v[78:81], v[154:157], v[206:209], v[78:81]
	v_mfma_f32_16x16x32_bf16 v[78:81], v[158:161], v[210:213], v[78:81]
	v_mfma_f32_16x16x32_bf16 v[66:69], v[154:157], v[214:217], v[66:69]
	v_mfma_f32_16x16x32_bf16 v[66:69], v[158:161], v[240:243], v[66:69]
	v_mfma_f32_16x16x32_bf16 v[70:73], v[146:149], v[214:217], v[70:73]
	v_mfma_f32_16x16x32_bf16 v[70:73], v[150:153], v[240:243], v[70:73]
	v_mfma_f32_16x16x32_bf16 v[74:77], v[138:141], v[214:217], v[74:77]
	v_mfma_f32_16x16x32_bf16 v[74:77], v[142:145], v[240:243], v[74:77]
	v_mfma_f32_16x16x32_bf16 v[82:85], v[130:133], v[214:217], v[82:85]
	v_mfma_f32_16x16x32_bf16 v[82:85], v[134:137], v[240:243], v[82:85]
	s_barrier
	s_setprio 0
	ds_read_b128 v[182:185], v180 offset:49152
	ds_read_b128 v[186:189], v180 offset:50176
	ds_read_b128 v[190:193], v180 offset:51200
	ds_read_b128 v[202:205], v180 offset:52224
	ds_read_b128 v[206:209], v180 offset:53248
	ds_read_b128 v[210:213], v180 offset:54272
	ds_read_b128 v[214:217], v180 offset:55296
	ds_read_b128 v[240:243], v180 offset:56320
	s_add_u32 s58, s58, 0x80
	s_addc_u32 s59, s59, 0
	s_mov_b32 m0, s89
	s_nop 0
	global_load_lds_dwordx4 v167, s[58:59]
	s_add_u32 s44, s44, 0x80
	s_mov_b32 m0, s95
	s_nop 0
	global_load_lds_dwordx4 v175, s[58:59]
	s_addc_u32 s45, s45, 0
	s_mov_b32 m0, s26
	s_nop 0
	global_load_lds_dwordx4 v167, s[44:45]
	s_nop 0
	s_mov_b32 m0, s27
	s_nop 0
	global_load_lds_dwordx4 v175, s[44:45]
	s_nop 0
	s_mov_b32 m0, s36
	s_nop 0
	global_load_lds_dwordx4 v165, s[56:57]
	s_nop 0
	s_mov_b32 m0, s37
	s_nop 0
	global_load_lds_dwordx4 v171, s[56:57]
	s_waitcnt vmcnt(8)
	s_waitcnt lgkmcnt(0)
	s_setprio 1
	s_barrier
	v_mfma_f32_16x16x32_bf16 v[62:65], v[130:133], v[182:185], v[62:65]
	v_mfma_f32_16x16x32_bf16 v[62:65], v[134:137], v[186:189], v[62:65]
	v_mfma_f32_16x16x32_bf16 v[58:61], v[138:141], v[182:185], v[58:61]
	v_mfma_f32_16x16x32_bf16 v[58:61], v[142:145], v[186:189], v[58:61]
	v_mfma_f32_16x16x32_bf16 v[54:57], v[146:149], v[182:185], v[54:57]
	v_mfma_f32_16x16x32_bf16 v[54:57], v[150:153], v[186:189], v[54:57]
	v_mfma_f32_16x16x32_bf16 v[50:53], v[154:157], v[182:185], v[50:53]
	v_mfma_f32_16x16x32_bf16 v[50:53], v[158:161], v[186:189], v[50:53]
	v_mfma_f32_16x16x32_bf16 v[30:33], v[154:157], v[190:193], v[30:33]
	v_mfma_f32_16x16x32_bf16 v[30:33], v[158:161], v[202:205], v[30:33]
	v_mfma_f32_16x16x32_bf16 v[38:41], v[146:149], v[190:193], v[38:41]
	v_mfma_f32_16x16x32_bf16 v[38:41], v[150:153], v[202:205], v[38:41]
	v_mfma_f32_16x16x32_bf16 v[42:45], v[138:141], v[190:193], v[42:45]
	v_mfma_f32_16x16x32_bf16 v[42:45], v[142:145], v[202:205], v[42:45]
	v_mfma_f32_16x16x32_bf16 v[46:49], v[130:133], v[190:193], v[46:49]
	v_mfma_f32_16x16x32_bf16 v[46:49], v[134:137], v[202:205], v[46:49]
	v_mfma_f32_16x16x32_bf16 v[34:37], v[130:133], v[206:209], v[34:37]
	v_mfma_f32_16x16x32_bf16 v[34:37], v[134:137], v[210:213], v[34:37]
	v_mfma_f32_16x16x32_bf16 v[26:29], v[138:141], v[206:209], v[26:29]
	v_mfma_f32_16x16x32_bf16 v[26:29], v[142:145], v[210:213], v[26:29]
	v_mfma_f32_16x16x32_bf16 v[22:25], v[146:149], v[206:209], v[22:25]
	v_mfma_f32_16x16x32_bf16 v[22:25], v[150:153], v[210:213], v[22:25]
	v_mfma_f32_16x16x32_bf16 v[14:17], v[154:157], v[206:209], v[14:17]
	v_mfma_f32_16x16x32_bf16 v[14:17], v[158:161], v[210:213], v[14:17]
	v_mfma_f32_16x16x32_bf16 v[2:5], v[154:157], v[214:217], v[2:5]
	v_mfma_f32_16x16x32_bf16 v[2:5], v[158:161], v[240:243], v[2:5]
	v_mfma_f32_16x16x32_bf16 v[6:9], v[146:149], v[214:217], v[6:9]
	v_mfma_f32_16x16x32_bf16 v[6:9], v[150:153], v[240:243], v[6:9]
	v_mfma_f32_16x16x32_bf16 v[10:13], v[138:141], v[214:217], v[10:13]
	v_mfma_f32_16x16x32_bf16 v[10:13], v[142:145], v[240:243], v[10:13]
	v_mfma_f32_16x16x32_bf16 v[18:21], v[130:133], v[214:217], v[18:21]
	v_mfma_f32_16x16x32_bf16 v[18:21], v[134:137], v[240:243], v[18:21]
	s_barrier
	s_setprio 0
	s_add_u32 s4, s4, 0x100
	s_addc_u32 s5, s5, 0
	s_add_u32 s0, s0, 0x100
	s_addc_u32 s1, s1, 0
	s_cmp_ge_u32 s55, s31
	s_mov_b32 s44, s55
	.p2align 6

; #define PG8_STAGE(bufoff, gbase, voff) do { _Pragma("unroll") for (int _i = 0; _i < 2; ++_i) { \
;         const unsigned _m0 = ldsb + (unsigned)((bufoff) + _i * 8192); const char* _gb = (const char*)(gbase); \
;         asm volatile("s_mov_b32 m0, %0\n\ts_nop 0\n\tglobal_load_lds_dwordx4 %1, %2" :: "s"(_m0), "v"((voff)[_i]), "s"(_gb) : "m0", "memory"); } } while (0)
; #define PG8_WAIT_V(n) asm volatile("s_waitcnt vmcnt(" #n ")" ::: "memory")
; #define PG8_WAIT_L(n) asm volatile("s_waitcnt lgkmcnt(" #n ")" ::: "memory")
; #define PG8_BAR __builtin_amdgcn_s_barrier()
;     __device__ bool next(int i, Unit& u) const {
;         const long L = (long)i * G + c; if (L >= nwg) return false;
;         int wgid = (int)L; { const int q = nwg / NXCD, r = nwg % NXCD, xcd = wgid % NXCD, off = wgid / NXCD; wgid = (xcd < r ? xcd * (q + 1) : r * (q + 1) + (xcd - r) * q) + off; }
;         const int nig = WGM * nN, gid = wgid / nig, fm = gid * WGM, gsz = (nM - fm) < WGM ? (nM - fm) : WGM;
;         u.pm = fm + ((wgid % nig) % gsz); u.pn = (wgid % nig) / gsz; return true;
; template <class Epi, bool ALIGN_EPI>
; __device__ __forceinline__ void gemm_phase(LAS unsigned char* lds, const Gemm g, const StaticOrder& S, const Epi& E) {
;     ...
;         const bool has_next = S.next(ui + 1, nxt);
;         const char* nA = has_next ? (const char*)g.A + (size_t)nxt.pm * tstepA + (size_t)nxt.pn * g.a_pn_off * 2 + (size_t)(nxt.pm >> 4) * g.a_adj : cA; const char* nB = has_next ? (const char*)g.Bt + (size_t)nxt.pn * tstepB : cB;
;         for (int t = 0; t < nt; t += 2) {
;             const bool last = (t == nt - 2);
;             const char* a1 = cA + (size_t)(t + 1) * kstep;
;             const char* a2 = last ? nA : cA + (size_t)(t + 2) * kstep; const char* b2 = last ? nB : cB + (size_t)(t + 2) * kstep;
;             const char* a3 = a2 + kstep; const char* b3 = b2 + kstep;
;             PG8_LDB(B0, 0, 0); PG8_LDB(B1, 0, 1); PG8_SCHED; PG8_LDA(At, 0, 0); PG8_STAGE(PG8_SA(1, 1), a1 + hstepA, voffA);
;             PG8_WAIT_V(8); PG8_WAIT_L(0); PG8_BAR; PG8_MMA(0, 0, At, B0); PG8_MMA(0, 1, At, B1); PG8_BAR; PG8_SCHED;
;             PG8_LDA(At, 0, 1); PG8_STAGE(PG8_SB(0, 0), b2, voffB); PG8_STAGE(PG8_SB(0, 1), b2 + hstepB, voffB); PG8_STAGE(PG8_SA(0, 0), a2, voffA);
;             PG8_WAIT_V(8); PG8_WAIT_L(0); PG8_BAR; PG8_MMA(1, 0, At, B0); PG8_MMA(1, 1, At, B1); PG8_BAR; PG8_SCHED;
.LBB0_305:
	s_add_u32 s41, s56, 0x100
	s_addc_u32 s49, s57, 0
	s_add_u32 s92, s58, 0x40080
	s_addc_u32 s93, s59, 0
	s_mov_b32 s50, -2
	s_add_u32 s30, s92, 0xfffc0080
	s_addc_u32 s31, s93, -1
	s_cmp_eq_u32 s50, 12
	s_cselect_b32 s60, s5, s30
	s_cselect_b32 s61, s4, s31
	s_cselect_b32 s58, s37, s41
	s_cselect_b32 s59, s35, s49
	s_add_u32 s56, s60, 0x80
	s_addc_u32 s57, s61, 0
	s_mov_b32 m0, s67
	s_nop 0
	global_load_lds_dwordx4 v0, s[92:93]
	s_nop 0
	s_mov_b32 m0, s65
	s_nop 0
	global_load_lds_dwordx4 v181, s[92:93]
	s_waitcnt vmcnt(8)
	s_waitcnt lgkmcnt(0)
	s_setprio 1
	s_barrier
	v_mfma_f32_16x16x32_bf16 v[142:145], v[74:77], v[162:165], 0
	v_mfma_f32_16x16x32_bf16 v[142:145], v[94:97], v[166:169], v[142:145]
	v_mfma_f32_16x16x32_bf16 v[138:141], v[114:117], v[162:165], 0
	v_mfma_f32_16x16x32_bf16 v[138:141], v[134:137], v[166:169], v[138:141]
	v_mfma_f32_16x16x32_bf16 v[130:133], v[146:149], v[162:165], 0
	v_mfma_f32_16x16x32_bf16 v[130:133], v[150:153], v[166:169], v[130:133]
	v_mfma_f32_16x16x32_bf16 v[126:129], v[154:157], v[162:165], 0
	v_mfma_f32_16x16x32_bf16 v[126:129], v[158:161], v[166:169], v[126:129]
	v_mfma_f32_16x16x32_bf16 v[106:109], v[154:157], v[170:173], 0
	v_mfma_f32_16x16x32_bf16 v[106:109], v[158:161], v[174:177], v[106:109]
	v_mfma_f32_16x16x32_bf16 v[110:113], v[146:149], v[170:173], 0
	v_mfma_f32_16x16x32_bf16 v[110:113], v[150:153], v[174:177], v[110:113]
	v_mfma_f32_16x16x32_bf16 v[118:121], v[114:117], v[170:173], 0
	v_mfma_f32_16x16x32_bf16 v[118:121], v[134:137], v[174:177], v[118:121]
	v_mfma_f32_16x16x32_bf16 v[122:125], v[74:77], v[170:173], 0
	v_mfma_f32_16x16x32_bf16 v[122:125], v[94:97], v[174:177], v[122:125]
	v_mfma_f32_16x16x32_bf16 v[102:105], v[74:77], v[188:191], 0
	v_mfma_f32_16x16x32_bf16 v[102:105], v[94:97], v[202:205], v[102:105]
	v_mfma_f32_16x16x32_bf16 v[98:101], v[114:117], v[188:191], 0
	v_mfma_f32_16x16x32_bf16 v[98:101], v[134:137], v[202:205], v[98:101]
	v_mfma_f32_16x16x32_bf16 v[90:93], v[146:149], v[188:191], 0
	v_mfma_f32_16x16x32_bf16 v[90:93], v[150:153], v[202:205], v[90:93]
	v_mfma_f32_16x16x32_bf16 v[86:89], v[154:157], v[188:191], 0
	v_mfma_f32_16x16x32_bf16 v[86:89], v[158:161], v[202:205], v[86:89]
	v_mfma_f32_16x16x32_bf16 v[66:69], v[154:157], v[206:209], 0
	v_mfma_f32_16x16x32_bf16 v[66:69], v[158:161], v[210:213], v[66:69]
	v_mfma_f32_16x16x32_bf16 v[70:73], v[146:149], v[206:209], 0
	v_mfma_f32_16x16x32_bf16 v[70:73], v[150:153], v[210:213], v[70:73]
	v_mfma_f32_16x16x32_bf16 v[78:81], v[114:117], v[206:209], 0
	v_mfma_f32_16x16x32_bf16 v[78:81], v[134:137], v[210:213], v[78:81]
	v_mfma_f32_16x16x32_bf16 v[82:85], v[74:77], v[206:209], 0
	v_mfma_f32_16x16x32_bf16 v[82:85], v[94:97], v[210:213], v[82:85]
	s_barrier
	s_setprio 0
	v_mbcnt_lo_u32_b32 v178, -1, 0
	v_mbcnt_hi_u32_b32 v178, -1, v178
	s_lshl_b32 s90, s54, 8
	s_add_i32 s90, s90, s89
	s_lshl_b32 s91, s89, 4
	s_add_i32 s91, s91, 0x23000
	v_add_lshl_u32 v178, v178, s90, 4
	s_mov_b32 m0, s91
	s_nop 0
	global_load_lds_dwordx4 v178, s[24:25]
	global_load_lds_dwordx4 v178, s[24:25] offset:2048
	ds_read_b128 v[162:165], v186 offset:16384
	ds_read_b128 v[166:169], v186 offset:17408
	ds_read_b128 v[170:173], v186 offset:18432
	ds_read_b128 v[174:177], v186 offset:19456
	ds_read_b128 v[188:191], v186 offset:20480
	ds_read_b128 v[202:205], v186 offset:21504
	ds_read_b128 v[206:209], v186 offset:22528
	ds_read_b128 v[210:213], v186 offset:23552
	s_mov_b32 m0, s29
	s_nop 0
	global_load_lds_dwordx4 v180, s[58:59]
	s_add_u32 s30, s58, 0x40000
	s_mov_b32 m0, s42
	s_nop 0
	global_load_lds_dwordx4 v182, s[58:59]
	s_addc_u32 s31, s59, 0
	s_mov_b32 m0, s43
	s_nop 0
	global_load_lds_dwordx4 v180, s[30:31]
	s_nop 0
	s_mov_b32 m0, s44
	s_nop 0
	global_load_lds_dwordx4 v182, s[30:31]
	s_nop 0
	s_mov_b32 m0, s15
	s_nop 0
	global_load_lds_dwordx4 v0, s[60:61]
	s_nop 0
	s_mov_b32 m0, s45
	s_nop 0
	global_load_lds_dwordx4 v181, s[60:61]
	s_mul_i32 s4, s85, s27
	s_mul_hi_u32 s5, s85, s87
	s_add_i32 s5, s5, s4
	s_mul_i32 s4, s85, s87
	s_add_u32 s4, s4, s16
	s_addc_u32 s5, s5, s68
	v_mov_b64_e32 v[192:193], s[46:47]
	v_cmp_lt_i64_e64 s[8:9], s[4:5], v[192:193]
	s_ashr_i32 s5, s4, 31
	s_lshr_b32 s5, s5, 29
	s_add_i32 s5, s4, s5
	s_ashr_i32 s90, s5, 3
	s_and_b32 s5, s5, -8
	s_sub_i32 s4, s4, s5
	s_lshr_b32 s5, s4, 31
	s_or_b32 s5, s78, s5
	s_mul_i32 s4, s5, s4
	s_add_i32 s4, s4, s90
	s_abs_i32 s90, s4
	v_readlane_b32 s91, v254, 48
	s_mul_hi_u32 s91, s90, s91
	s_mul_i32 s34, s91, s26
	s_sub_i32 s90, s90, s34
	s_ashr_i32 s5, s4, 31
	s_add_i32 s34, s91, 1
	s_sub_i32 s35, s90, s26
	s_cmp_ge_u32 s90, s26
	s_cselect_b32 s91, s34, s91
	s_cselect_b32 s90, s35, s90
	s_waitcnt vmcnt(8)
	s_waitcnt lgkmcnt(0)
	s_setprio 1
	s_barrier
; #define PG8_STAGE(bufoff, gbase, voff) do { _Pragma("unroll") for (int _i = 0; _i < 2; ++_i) { \
;         const unsigned _m0 = ldsb + (unsigned)((bufoff) + _i * 8192); const char* _gb = (const char*)(gbase); \
;         asm volatile("s_mov_b32 m0, %0\n\ts_nop 0\n\tglobal_load_lds_dwordx4 %1, %2" :: "s"(_m0), "v"((voff)[_i]), "s"(_gb) : "m0", "memory"); } } while (0)
; #define PG8_LDA(dst, b, h) do { _Pragma("unroll") for (int m = 0; m < 4; ++m) _Pragma("unroll") for (int k = 0; k < 2; ++k) dst[m][k] = *(const LAS bf16x8*)(lds + PG8_SA(b, h) + aoff + m * 2048 + k * 1024); } while (0)
; #define PG8_LDB(dst, b, h) do { _Pragma("unroll") for (int n = 0; n < 2; ++n) _Pragma("unroll") for (int k = 0; k < 2; ++k) dst[n][k] = *(const LAS bf16x8*)(lds + PG8_SB(b, h) + boff + n * 2048 + k * 1024); } while (0)
; #define PG8_MMA(ai, bj, At, Bt) do { __builtin_amdgcn_s_setprio(1); _Pragma("unroll") for (int m = 0; m < 4; ++m) _Pragma("unroll") for (int n = 0; n < 2; ++n) _Pragma("unroll") for (int k = 0; k < 2; ++k) \
;         acc[ai][bj][m][n] = __builtin_amdgcn_mfma_f32_16x16x32_bf16(Bt[n][k], At[m][k], acc[ai][bj][m][n], 0, 0, 0); __builtin_amdgcn_s_setprio(0); } while (0)
; #define PG8_WAIT_V(n) asm volatile("s_waitcnt vmcnt(" #n ")" ::: "memory")
; #define PG8_WAIT_L(n) asm volatile("s_waitcnt lgkmcnt(" #n ")" ::: "memory")
; #define PG8_BAR __builtin_amdgcn_s_barrier()
; #define PG8_SCHED __builtin_amdgcn_sched_barrier(0)
;     __device__ bool next(int i, Unit& u) const {
;     ...
;         int wgid = (int)L; { const int q = nwg / NXCD, r = nwg % NXCD, xcd = wgid % NXCD, off = wgid / NXCD; wgid = (xcd < r ? xcd * (q + 1) : r * (q + 1) + (xcd - r) * q) + off; }
;         const int nig = WGM * nN, gid = wgid / nig, fm = gid * WGM, gsz = (nM - fm) < WGM ? (nM - fm) : WGM;
;         u.pm = fm + ((wgid % nig) % gsz); u.pn = (wgid % nig) / gsz; return true;
; template <class Epi, bool ALIGN_EPI>
; __device__ __forceinline__ void gemm_phase(LAS unsigned char* lds, const Gemm g, const StaticOrder& S, const Epi& E) {
;     ...
;             PG8_WAIT_V(8); PG8_WAIT_L(0); PG8_BAR; PG8_MMA(1, 0, At, B0); PG8_MMA(1, 1, At, B1); PG8_BAR; PG8_SCHED;
;             PG8_LDB(B0, 1, 0); PG8_LDB(B1, 1, 1); PG8_SCHED; PG8_LDA(At, 1, 0); PG8_STAGE(PG8_SA(0, 1), a2 + hstepA, voffA);
;             PG8_WAIT_V(8); PG8_WAIT_L(0); PG8_BAR; PG8_MMA(0, 0, At, B0); PG8_MMA(0, 1, At, B1); PG8_BAR; PG8_SCHED;
	v_mfma_f32_16x16x32_bf16 v[62:65], v[74:77], v[162:165], 0
	v_mfma_f32_16x16x32_bf16 v[62:65], v[94:97], v[166:169], v[62:65]
	v_mfma_f32_16x16x32_bf16 v[58:61], v[114:117], v[162:165], 0
	v_mfma_f32_16x16x32_bf16 v[58:61], v[134:137], v[166:169], v[58:61]
	v_mfma_f32_16x16x32_bf16 v[54:57], v[146:149], v[162:165], 0
	v_mfma_f32_16x16x32_bf16 v[54:57], v[150:153], v[166:169], v[54:57]
	v_mfma_f32_16x16x32_bf16 v[50:53], v[154:157], v[162:165], 0
	v_mfma_f32_16x16x32_bf16 v[50:53], v[158:161], v[166:169], v[50:53]
	v_mfma_f32_16x16x32_bf16 v[34:37], v[154:157], v[170:173], 0
	v_mfma_f32_16x16x32_bf16 v[34:37], v[158:161], v[174:177], v[34:37]
	v_mfma_f32_16x16x32_bf16 v[38:41], v[146:149], v[170:173], 0
	v_mfma_f32_16x16x32_bf16 v[38:41], v[150:153], v[174:177], v[38:41]
	v_mfma_f32_16x16x32_bf16 v[42:45], v[114:117], v[170:173], 0
	v_mfma_f32_16x16x32_bf16 v[42:45], v[134:137], v[174:177], v[42:45]
	v_mfma_f32_16x16x32_bf16 v[46:49], v[74:77], v[170:173], 0
	v_mfma_f32_16x16x32_bf16 v[46:49], v[94:97], v[174:177], v[46:49]
	v_mfma_f32_16x16x32_bf16 v[30:33], v[74:77], v[188:191], 0
	v_mfma_f32_16x16x32_bf16 v[30:33], v[94:97], v[202:205], v[30:33]
	v_mfma_f32_16x16x32_bf16 v[26:29], v[114:117], v[188:191], 0
	v_mfma_f32_16x16x32_bf16 v[26:29], v[134:137], v[202:205], v[26:29]
	v_mfma_f32_16x16x32_bf16 v[22:25], v[146:149], v[188:191], 0
	v_mfma_f32_16x16x32_bf16 v[22:25], v[150:153], v[202:205], v[22:25]
	v_mfma_f32_16x16x32_bf16 v[18:21], v[154:157], v[188:191], 0
	v_mfma_f32_16x16x32_bf16 v[18:21], v[158:161], v[202:205], v[18:21]
	v_mfma_f32_16x16x32_bf16 v[2:5], v[154:157], v[206:209], 0
	v_mfma_f32_16x16x32_bf16 v[2:5], v[158:161], v[210:213], v[2:5]
	v_mfma_f32_16x16x32_bf16 v[6:9], v[146:149], v[206:209], 0
	v_mfma_f32_16x16x32_bf16 v[6:9], v[150:153], v[210:213], v[6:9]
	v_mfma_f32_16x16x32_bf16 v[10:13], v[114:117], v[206:209], 0
	v_mfma_f32_16x16x32_bf16 v[10:13], v[134:137], v[210:213], v[10:13]
	v_mfma_f32_16x16x32_bf16 v[14:17], v[74:77], v[206:209], 0
	v_mfma_f32_16x16x32_bf16 v[14:17], v[94:97], v[210:213], v[14:17]
	s_barrier
	s_setprio 0
	v_add_u32_e32 v134, 0x18000, v185
	v_add_u32_e32 v158, 0x1c000, v185
	ds_read_b128 v[74:77], v134
	ds_read_b128 v[94:97], v134 offset:1024
	ds_read_b128 v[114:117], v134 offset:2048
	ds_read_b128 v[134:137], v134 offset:3072
	ds_read_b128 v[146:149], v158
	ds_read_b128 v[150:153], v158 offset:1024
	ds_read_b128 v[154:157], v158 offset:2048
	ds_read_b128 v[158:161], v158 offset:3072
	ds_read_b128 v[162:165], v186 offset:32768
	ds_read_b128 v[166:169], v186 offset:33792
	ds_read_b128 v[170:173], v186 offset:34816
	ds_read_b128 v[174:177], v186 offset:35840
	ds_read_b128 v[188:191], v186 offset:36864
	ds_read_b128 v[202:205], v186 offset:37888
	ds_read_b128 v[206:209], v186 offset:38912
	ds_read_b128 v[210:213], v186 offset:39936
	s_add_u32 s30, s60, 0x40000
	s_addc_u32 s31, s61, 0
	s_mov_b32 m0, s55
	s_nop 0
	global_load_lds_dwordx4 v0, s[30:31]
	s_nop 0
	s_mov_b32 m0, s88
	s_nop 0
	global_load_lds_dwordx4 v181, s[30:31]
	s_add_i32 s34, s91, 1
	s_cmp_ge_u32 s90, s26
	s_cselect_b32 s90, s34, s91
	s_xor_b32 s90, s90, s5
	s_sub_i32 s5, s90, s5
	s_lshl_b32 s90, s5, 3
	s_sub_i32 s91, 0x80, s90
	s_min_i32 s91, s91, 8
	s_mul_i32 s5, s5, s26
	s_sub_i32 s4, s4, s5
	s_lshr_b32 s34, s4, 3
	s_and_b32 s4, s4, 7
	s_waitcnt vmcnt(8)
	s_waitcnt lgkmcnt(0)
	s_setprio 1
	s_barrier
	v_mfma_f32_16x16x32_bf16 v[142:145], v[74:77], v[162:165], v[142:145]
	v_mfma_f32_16x16x32_bf16 v[142:145], v[94:97], v[166:169], v[142:145]
	v_mfma_f32_16x16x32_bf16 v[138:141], v[114:117], v[162:165], v[138:141]
	v_mfma_f32_16x16x32_bf16 v[138:141], v[134:137], v[166:169], v[138:141]
	v_mfma_f32_16x16x32_bf16 v[130:133], v[146:149], v[162:165], v[130:133]
	v_mfma_f32_16x16x32_bf16 v[130:133], v[150:153], v[166:169], v[130:133]
	v_mfma_f32_16x16x32_bf16 v[126:129], v[154:157], v[162:165], v[126:129]
	v_mfma_f32_16x16x32_bf16 v[126:129], v[158:161], v[166:169], v[126:129]
	v_mfma_f32_16x16x32_bf16 v[106:109], v[154:157], v[170:173], v[106:109]
	v_mfma_f32_16x16x32_bf16 v[106:109], v[158:161], v[174:177], v[106:109]
	v_mfma_f32_16x16x32_bf16 v[110:113], v[146:149], v[170:173], v[110:113]
	v_mfma_f32_16x16x32_bf16 v[110:113], v[150:153], v[174:177], v[110:113]
	v_mfma_f32_16x16x32_bf16 v[118:121], v[114:117], v[170:173], v[118:121]
	v_mfma_f32_16x16x32_bf16 v[118:121], v[134:137], v[174:177], v[118:121]
	v_mfma_f32_16x16x32_bf16 v[122:125], v[74:77], v[170:173], v[122:125]
	v_mfma_f32_16x16x32_bf16 v[122:125], v[94:97], v[174:177], v[122:125]
	v_mfma_f32_16x16x32_bf16 v[102:105], v[74:77], v[188:191], v[102:105]
	v_mfma_f32_16x16x32_bf16 v[102:105], v[94:97], v[202:205], v[102:105]
	v_mfma_f32_16x16x32_bf16 v[98:101], v[114:117], v[188:191], v[98:101]
	v_mfma_f32_16x16x32_bf16 v[98:101], v[134:137], v[202:205], v[98:101]
	v_mfma_f32_16x16x32_bf16 v[90:93], v[146:149], v[188:191], v[90:93]
	v_mfma_f32_16x16x32_bf16 v[90:93], v[150:153], v[202:205], v[90:93]
	v_mfma_f32_16x16x32_bf16 v[86:89], v[154:157], v[188:191], v[86:89]
	v_mfma_f32_16x16x32_bf16 v[86:89], v[158:161], v[202:205], v[86:89]
	v_mfma_f32_16x16x32_bf16 v[66:69], v[154:157], v[206:209], v[66:69]
	v_mfma_f32_16x16x32_bf16 v[66:69], v[158:161], v[210:213], v[66:69]
	v_mfma_f32_16x16x32_bf16 v[70:73], v[146:149], v[206:209], v[70:73]
	v_mfma_f32_16x16x32_bf16 v[70:73], v[150:153], v[210:213], v[70:73]
	v_mfma_f32_16x16x32_bf16 v[78:81], v[114:117], v[206:209], v[78:81]
	v_mfma_f32_16x16x32_bf16 v[78:81], v[134:137], v[210:213], v[78:81]
	v_mfma_f32_16x16x32_bf16 v[82:85], v[74:77], v[206:209], v[82:85]
	v_mfma_f32_16x16x32_bf16 v[82:85], v[94:97], v[210:213], v[82:85]
	s_barrier
; #define PG8_STAGE(bufoff, gbase, voff) do { _Pragma("unroll") for (int _i = 0; _i < 2; ++_i) { \
;         const unsigned _m0 = ldsb + (unsigned)((bufoff) + _i * 8192); const char* _gb = (const char*)(gbase); \
;         asm volatile("s_mov_b32 m0, %0\n\ts_nop 0\n\tglobal_load_lds_dwordx4 %1, %2" :: "s"(_m0), "v"((voff)[_i]), "s"(_gb) : "m0", "memory"); } } while (0)
; #define PG8_LDA(dst, b, h) do { _Pragma("unroll") for (int m = 0; m < 4; ++m) _Pragma("unroll") for (int k = 0; k < 2; ++k) dst[m][k] = *(const LAS bf16x8*)(lds + PG8_SA(b, h) + aoff + m * 2048 + k * 1024); } while (0)
; #define PG8_MMA(ai, bj, At, Bt) do { __builtin_amdgcn_s_setprio(1); _Pragma("unroll") for (int m = 0; m < 4; ++m) _Pragma("unroll") for (int n = 0; n < 2; ++n) _Pragma("unroll") for (int k = 0; k < 2; ++k) \
;         acc[ai][bj][m][n] = __builtin_amdgcn_mfma_f32_16x16x32_bf16(Bt[n][k], At[m][k], acc[ai][bj][m][n], 0, 0, 0); __builtin_amdgcn_s_setprio(0); } while (0)
; #define PG8_WAIT_V(n) asm volatile("s_waitcnt vmcnt(" #n ")" ::: "memory")
; #define PG8_WAIT_L(n) asm volatile("s_waitcnt lgkmcnt(" #n ")" ::: "memory")
; #define PG8_BAR __builtin_amdgcn_s_barrier()
; #define PG8_SCHED __builtin_amdgcn_sched_barrier(0)
; template <class Epi, bool ALIGN_EPI>
; __device__ __forceinline__ void gemm_phase(LAS unsigned char* lds, const Gemm g, const StaticOrder& S, const Epi& E) {
;     ...
;         const char* nA = has_next ? (const char*)g.A + (size_t)nxt.pm * tstepA + (size_t)nxt.pn * g.a_pn_off * 2 + (size_t)(nxt.pm >> 4) * g.a_adj : cA; const char* nB = has_next ? (const char*)g.Bt + (size_t)nxt.pn * tstepB : cB;
;     ...
;             PG8_LDA(At, 1, 1); PG8_STAGE(PG8_SB(1, 0), b3, voffB); PG8_STAGE(PG8_SB(1, 1), b3 + hstepB, voffB); PG8_STAGE(PG8_SA(1, 0), a3, voffA);
;             PG8_WAIT_V(8); PG8_WAIT_L(0); PG8_BAR; PG8_MMA(1, 0, At, B0); PG8_MMA(1, 1, At, B1); PG8_BAR; PG8_SCHED;
;         }
	s_setprio 0
	ds_read_b128 v[162:165], v186 offset:49152
	ds_read_b128 v[166:169], v186 offset:50176
	ds_read_b128 v[170:173], v186 offset:51200
	ds_read_b128 v[174:177], v186 offset:52224
	ds_read_b128 v[188:191], v186 offset:53248
	ds_read_b128 v[202:205], v186 offset:54272
	ds_read_b128 v[206:209], v186 offset:55296
	ds_read_b128 v[210:213], v186 offset:56320
	s_add_u32 s30, s58, 0x80
	s_addc_u32 s31, s59, 0
	s_mov_b32 m0, s94
	s_nop 0
	global_load_lds_dwordx4 v180, s[30:31]
	s_nop 0
	s_mov_b32 m0, s95
	s_nop 0
	global_load_lds_dwordx4 v182, s[30:31]
	s_add_u32 s30, s58, 0x40080
	s_addc_u32 s31, s59, 0
	s_mov_b32 m0, s17
	s_nop 0
	global_load_lds_dwordx4 v180, s[30:31]
	s_nop 0
	s_mov_b32 m0, s53
	s_nop 0
	global_load_lds_dwordx4 v182, s[30:31]
	s_nop 0
	s_mov_b32 m0, s96
	s_nop 0
	global_load_lds_dwordx4 v0, s[56:57]
	s_nop 0
	s_mov_b32 m0, s97
	s_nop 0
	global_load_lds_dwordx4 v181, s[56:57]
	s_add_i32 s36, s4, s90
	s_ashr_i32 s37, s36, 31
	s_lshl_b64 s[4:5], s[36:37], 19
	s_add_u32 s38, s18, s4
	s_addc_u32 s39, s19, s5
	s_and_b64 s[4:5], s[8:9], exec
	s_cselect_b32 s4, s39, s59
	s_cselect_b32 s5, s38, s58
	s_ashr_i32 s35, s34, 31
	s_lshl_b64 vcc, s[34:35], 19
	s_add_u32 s90, s1, vcc_lo
	s_addc_u32 s91, s14, vcc_hi
	s_and_b64 vcc, s[8:9], exec
	s_cselect_b32 s35, s91, s57
	s_cselect_b32 s37, s90, s56
	s_waitcnt vmcnt(8)
	s_waitcnt lgkmcnt(0)
	s_setprio 1
	s_barrier
	v_mfma_f32_16x16x32_bf16 v[62:65], v[74:77], v[162:165], v[62:65]
	v_mfma_f32_16x16x32_bf16 v[62:65], v[94:97], v[166:169], v[62:65]
	v_mfma_f32_16x16x32_bf16 v[58:61], v[114:117], v[162:165], v[58:61]
	v_mfma_f32_16x16x32_bf16 v[58:61], v[134:137], v[166:169], v[58:61]
	v_mfma_f32_16x16x32_bf16 v[54:57], v[146:149], v[162:165], v[54:57]
	v_mfma_f32_16x16x32_bf16 v[54:57], v[150:153], v[166:169], v[54:57]
	v_mfma_f32_16x16x32_bf16 v[50:53], v[154:157], v[162:165], v[50:53]
	v_mfma_f32_16x16x32_bf16 v[50:53], v[158:161], v[166:169], v[50:53]
	v_mfma_f32_16x16x32_bf16 v[34:37], v[154:157], v[170:173], v[34:37]
	v_mfma_f32_16x16x32_bf16 v[34:37], v[158:161], v[174:177], v[34:37]
	v_mfma_f32_16x16x32_bf16 v[38:41], v[146:149], v[170:173], v[38:41]
	v_mfma_f32_16x16x32_bf16 v[38:41], v[150:153], v[174:177], v[38:41]
	v_mfma_f32_16x16x32_bf16 v[42:45], v[114:117], v[170:173], v[42:45]
	v_mfma_f32_16x16x32_bf16 v[42:45], v[134:137], v[174:177], v[42:45]
	v_mfma_f32_16x16x32_bf16 v[46:49], v[74:77], v[170:173], v[46:49]
	v_mfma_f32_16x16x32_bf16 v[46:49], v[94:97], v[174:177], v[46:49]
	v_mfma_f32_16x16x32_bf16 v[30:33], v[74:77], v[188:191], v[30:33]
	v_mfma_f32_16x16x32_bf16 v[30:33], v[94:97], v[202:205], v[30:33]
	v_mfma_f32_16x16x32_bf16 v[26:29], v[114:117], v[188:191], v[26:29]
	v_mfma_f32_16x16x32_bf16 v[26:29], v[134:137], v[202:205], v[26:29]
	v_mfma_f32_16x16x32_bf16 v[22:25], v[146:149], v[188:191], v[22:25]
	v_mfma_f32_16x16x32_bf16 v[22:25], v[150:153], v[202:205], v[22:25]
	v_mfma_f32_16x16x32_bf16 v[18:21], v[154:157], v[188:191], v[18:21]
	v_mfma_f32_16x16x32_bf16 v[18:21], v[158:161], v[202:205], v[18:21]
	v_mfma_f32_16x16x32_bf16 v[2:5], v[154:157], v[206:209], v[2:5]
	v_mfma_f32_16x16x32_bf16 v[2:5], v[158:161], v[210:213], v[2:5]
	v_mfma_f32_16x16x32_bf16 v[6:9], v[146:149], v[206:209], v[6:9]
	v_mfma_f32_16x16x32_bf16 v[6:9], v[150:153], v[210:213], v[6:9]
	v_mfma_f32_16x16x32_bf16 v[10:13], v[114:117], v[206:209], v[10:13]
	v_mfma_f32_16x16x32_bf16 v[10:13], v[134:137], v[210:213], v[10:13]
	v_mfma_f32_16x16x32_bf16 v[14:17], v[74:77], v[206:209], v[14:17]
	v_mfma_f32_16x16x32_bf16 v[14:17], v[94:97], v[210:213], v[14:17]
	s_barrier
	s_setprio 0
	s_add_i32 s50, s50, 2
	s_add_u32 s41, s41, 0x100
	s_addc_u32 s49, s49, 0
	s_add_u32 s92, s92, 0x100
	s_addc_u32 s93, s93, 0
	s_cmp_gt_u32 s50, 13
	.p2align 6

; template <class Epi, bool ALIGN_EPI>
; __device__ __forceinline__ void gemm_phase(LAS unsigned char* lds, const Gemm g, const StaticOrder& S, const Epi& E) {
;     ...
;         const bool has_next = S.next(ui + 1, nxt);
;         const char* nA = has_next ? (const char*)g.A + (size_t)nxt.pm * tstepA + (size_t)nxt.pn * g.a_pn_off * 2 + (size_t)(nxt.pm >> 4) * g.a_adj : cA; const char* nB = has_next ? (const char*)g.Bt + (size_t)nxt.pn * tstepB : cB;
;     ...
; #pragma unroll
;         for (int a = 0; a < 2; ++a)
; #pragma unroll
;             for (int b = 0; b < 2; ++b)
; #pragma unroll
;                 for (int m = 0; m < 4; ++m)
; #pragma unroll
;                     for (int n = 0; n < 2; ++n) acc[a][b][m][n] = (f32x4){0.f, 0.f, 0.f, 0.f};
;         cur = nxt; cA = nA; cB = nB; ++ui;
.LBB0_348:
	s_ashr_i32 s29, s28, 31
	s_lshl_b64 s[4:5], s[28:29], 19
	s_add_u32 s30, s18, s4
	s_addc_u32 s31, s19, s5
	s_and_b64 s[4:5], s[8:9], exec
	s_cselect_b32 s4, s31, s39
	s_cselect_b32 s5, s30, s38
	s_ashr_i32 s27, s26, 31
	s_lshl_b64 s[34:35], s[26:27], 19
	s_add_u32 s34, s14, s34
	s_addc_u32 s35, s15, s35
	s_and_b64 s[48:49], s[8:9], exec
	s_cselect_b32 s11, s35, s37
	s_cselect_b32 s27, s34, s36
	s_add_u32 s29, s36, 0x100
	s_addc_u32 s41, s37, 0
	s_add_u32 s36, s38, 0x40080
	v_mov_b32_e32 v2, 0
	s_addc_u32 s37, s39, 0
	s_mov_b32 s50, -2
	v_mov_b32_e32 v3, v2
	v_mov_b32_e32 v4, v2
	v_mov_b32_e32 v5, v2
	v_mov_b32_e32 v6, v2
	v_mov_b32_e32 v7, v2
	v_mov_b32_e32 v8, v2
	v_mov_b32_e32 v9, v2
	v_mov_b32_e32 v18, v2
	v_mov_b32_e32 v19, v2
	v_mov_b32_e32 v20, v2
	v_mov_b32_e32 v21, v2
	v_mov_b32_e32 v22, v2
	v_mov_b32_e32 v23, v2
	v_mov_b32_e32 v24, v2
	v_mov_b32_e32 v25, v2
	v_mov_b32_e32 v38, v2
	v_mov_b32_e32 v39, v2
	v_mov_b32_e32 v40, v2
	v_mov_b32_e32 v41, v2
	v_mov_b32_e32 v42, v2
	v_mov_b32_e32 v43, v2
	v_mov_b32_e32 v44, v2
	v_mov_b32_e32 v45, v2
	v_mov_b32_e32 v58, v2
	v_mov_b32_e32 v59, v2
	v_mov_b32_e32 v60, v2
	v_mov_b32_e32 v61, v2
	v_mov_b32_e32 v62, v2
	v_mov_b32_e32 v63, v2
	v_mov_b32_e32 v64, v2
	v_mov_b32_e32 v65, v2
	v_mov_b32_e32 v10, v2
	v_mov_b32_e32 v11, v2
	v_mov_b32_e32 v12, v2
	v_mov_b32_e32 v13, v2
	v_mov_b32_e32 v14, v2
	v_mov_b32_e32 v15, v2
	v_mov_b32_e32 v16, v2
	v_mov_b32_e32 v17, v2
	v_mov_b32_e32 v26, v2
	v_mov_b32_e32 v27, v2
	v_mov_b32_e32 v28, v2
	v_mov_b32_e32 v29, v2
	v_mov_b32_e32 v30, v2
	v_mov_b32_e32 v31, v2
	v_mov_b32_e32 v32, v2
	v_mov_b32_e32 v33, v2
	v_mov_b32_e32 v46, v2
	v_mov_b32_e32 v47, v2
	v_mov_b32_e32 v48, v2
	v_mov_b32_e32 v49, v2
	v_mov_b32_e32 v50, v2
	v_mov_b32_e32 v51, v2
	v_mov_b32_e32 v52, v2
	v_mov_b32_e32 v53, v2
	v_mov_b32_e32 v66, v2
	v_mov_b32_e32 v67, v2
	v_mov_b32_e32 v68, v2
	v_mov_b32_e32 v69, v2
	v_mov_b32_e32 v70, v2
	v_mov_b32_e32 v71, v2
	v_mov_b32_e32 v72, v2
	v_mov_b32_e32 v73, v2
	v_mov_b32_e32 v78, v2
	v_mov_b32_e32 v79, v2
	v_mov_b32_e32 v80, v2
	v_mov_b32_e32 v81, v2
	v_mov_b32_e32 v82, v2
	v_mov_b32_e32 v83, v2
	v_mov_b32_e32 v84, v2
	v_mov_b32_e32 v85, v2
	v_mov_b32_e32 v98, v2
	v_mov_b32_e32 v99, v2
	v_mov_b32_e32 v100, v2
	v_mov_b32_e32 v101, v2
	v_mov_b32_e32 v102, v2
	v_mov_b32_e32 v103, v2
	v_mov_b32_e32 v104, v2
	v_mov_b32_e32 v105, v2
	v_mov_b32_e32 v118, v2
	v_mov_b32_e32 v119, v2
	v_mov_b32_e32 v120, v2
	v_mov_b32_e32 v121, v2
	v_mov_b32_e32 v122, v2
	v_mov_b32_e32 v123, v2
	v_mov_b32_e32 v124, v2
	v_mov_b32_e32 v125, v2
	v_mov_b32_e32 v138, v2
	v_mov_b32_e32 v139, v2
	v_mov_b32_e32 v140, v2
	v_mov_b32_e32 v141, v2
	v_mov_b32_e32 v142, v2
	v_mov_b32_e32 v143, v2
	v_mov_b32_e32 v144, v2
	v_mov_b32_e32 v145, v2
	v_mov_b32_e32 v86, v2
	v_mov_b32_e32 v87, v2
	v_mov_b32_e32 v88, v2
	v_mov_b32_e32 v89, v2
	v_mov_b32_e32 v90, v2
	v_mov_b32_e32 v91, v2
	v_mov_b32_e32 v92, v2
	v_mov_b32_e32 v93, v2
	v_mov_b32_e32 v106, v2
	v_mov_b32_e32 v107, v2
	v_mov_b32_e32 v108, v2
	v_mov_b32_e32 v109, v2
	v_mov_b32_e32 v114, v2
	v_mov_b32_e32 v115, v2
	v_mov_b32_e32 v116, v2
	v_mov_b32_e32 v117, v2
	v_mov_b32_e32 v130, v2
	v_mov_b32_e32 v131, v2
	v_mov_b32_e32 v132, v2
	v_mov_b32_e32 v133, v2
	v_mov_b32_e32 v134, v2
	v_mov_b32_e32 v135, v2
	v_mov_b32_e32 v136, v2
	v_mov_b32_e32 v137, v2
	v_mov_b32_e32 v150, v2
	v_mov_b32_e32 v151, v2
	v_mov_b32_e32 v152, v2
	v_mov_b32_e32 v153, v2
	v_mov_b32_e32 v154, v2
	v_mov_b32_e32 v155, v2
	v_mov_b32_e32 v156, v2
	v_mov_b32_e32 v157, v2
	.p2align 6
